# GEMM loops: the redundant lgkmcnt(0) after each pre-MFMA barrier moved in front of that barrier (one issue slot less between barrier release and the first MFMA)
# speedup vs baseline: 1.0079x; 1.0030x over previous
.LBB0_145:
	s_add_u32 s27, s50, 0x100
	s_addc_u32 s56, s51, 0
	s_mov_b32 s57, -2
	s_waitcnt lgkmcnt(0)
	ds_read_b128 v[128:131], v188
	ds_read_b128 v[132:135], v188 offset:1024
	ds_read_b128 v[136:139], v188 offset:2048
	ds_read_b128 v[140:143], v188 offset:3072
	ds_read_b128 v[144:147], v189
	ds_read_b128 v[148:151], v189 offset:1024
	ds_read_b128 v[176:179], v189 offset:2048
	ds_read_b128 v[180:183], v189 offset:3072
	s_add_u32 s50, s48, 0x100
	s_addc_u32 s51, s49, 0
	s_cmp_eq_u32 s57, 28
	s_cselect_b32 s55, s21, s51
	s_cselect_b32 s54, s20, s50
	s_cselect_b32 s53, s23, s56
	s_cselect_b32 s52, s22, s27
	v_lshl_add_u64 v[184:185], s[48:49], 0, v[170:171]
	s_add_i32 m0, s60, 0xc000
	ds_read_b128 v[194:197], v190
	ds_read_b128 v[198:201], v190 offset:1024
	ds_read_b128 v[202:205], v190 offset:2048
	ds_read_b128 v[206:209], v190 offset:3072
	ds_read_b128 v[210:213], v190 offset:4096
	ds_read_b128 v[214:217], v190 offset:5120
	ds_read_b128 v[218:221], v190 offset:6144
	ds_read_b128 v[222:225], v190 offset:7168
	global_load_lds_dwordx4 v[184:185], off
	v_lshl_add_u64 v[184:185], s[48:49], 0, v[172:173]
	s_add_i32 m0, s60, 0xe000
	s_nop 0
	global_load_lds_dwordx4 v[184:185], off
	s_waitcnt vmcnt(8)
	s_waitcnt lgkmcnt(0)
	s_waitcnt lgkmcnt(0)
	s_barrier
	s_setprio 1
	v_mfma_f32_16x16x32_bf16 v[120:123], v[128:131], v[194:197], 0
	v_mfma_f32_16x16x32_bf16 v[124:127], v[136:139], v[194:197], 0
	v_mfma_f32_16x16x32_bf16 v[108:111], v[128:131], v[202:205], 0
	v_mfma_f32_16x16x32_bf16 v[104:107], v[136:139], v[202:205], 0
	v_mfma_f32_16x16x32_bf16 v[92:95], v[128:131], v[210:213], 0
	v_mfma_f32_16x16x32_bf16 v[88:91], v[136:139], v[210:213], 0
	v_mfma_f32_16x16x32_bf16 v[76:79], v[128:131], v[218:221], 0
	v_mfma_f32_16x16x32_bf16 v[72:75], v[136:139], v[218:221], 0
	v_mfma_f32_16x16x32_bf16 v[120:123], v[132:135], v[198:201], v[120:123]
	v_mfma_f32_16x16x32_bf16 v[124:127], v[140:143], v[198:201], v[124:127]
	v_mfma_f32_16x16x32_bf16 v[108:111], v[132:135], v[206:209], v[108:111]
	v_mfma_f32_16x16x32_bf16 v[104:107], v[140:143], v[206:209], v[104:107]
	v_mfma_f32_16x16x32_bf16 v[92:95], v[132:135], v[214:217], v[92:95]
	v_mfma_f32_16x16x32_bf16 v[88:91], v[140:143], v[214:217], v[88:91]
	v_mfma_f32_16x16x32_bf16 v[76:79], v[132:135], v[222:225], v[76:79]
	v_mfma_f32_16x16x32_bf16 v[72:75], v[140:143], v[222:225], v[72:75]
	s_setprio 0
	s_setprio 1
	v_mfma_f32_16x16x32_bf16 v[112:115], v[144:147], v[194:197], 0
	v_mfma_f32_16x16x32_bf16 v[116:119], v[176:179], v[194:197], 0
	v_mfma_f32_16x16x32_bf16 v[100:103], v[144:147], v[202:205], 0
	v_mfma_f32_16x16x32_bf16 v[96:99], v[176:179], v[202:205], 0
	v_mfma_f32_16x16x32_bf16 v[84:87], v[144:147], v[210:213], 0
	v_mfma_f32_16x16x32_bf16 v[80:83], v[176:179], v[210:213], 0
	v_mfma_f32_16x16x32_bf16 v[68:71], v[144:147], v[218:221], 0
	v_mfma_f32_16x16x32_bf16 v[64:67], v[176:179], v[218:221], 0
	v_mfma_f32_16x16x32_bf16 v[112:115], v[148:151], v[198:201], v[112:115]
	v_mfma_f32_16x16x32_bf16 v[116:119], v[180:183], v[198:201], v[116:119]
	v_mfma_f32_16x16x32_bf16 v[100:103], v[148:151], v[206:209], v[100:103]
	v_mfma_f32_16x16x32_bf16 v[96:99], v[180:183], v[206:209], v[96:99]
	v_mfma_f32_16x16x32_bf16 v[84:87], v[148:151], v[214:217], v[84:87]
	v_mfma_f32_16x16x32_bf16 v[80:83], v[180:183], v[214:217], v[80:83]
	v_mfma_f32_16x16x32_bf16 v[68:71], v[148:151], v[222:225], v[68:71]
	v_mfma_f32_16x16x32_bf16 v[64:67], v[180:183], v[222:225], v[64:67]
	s_setprio 0
	s_barrier
	s_add_i32 s48, s71, s3
	v_lshl_add_u64 v[184:185], s[52:53], 0, v[154:155]
	s_mov_b32 m0, s48
	ds_read_b128 v[194:197], v190 offset:16384
	ds_read_b128 v[198:201], v190 offset:17408
	ds_read_b128 v[202:205], v190 offset:18432
	ds_read_b128 v[206:209], v190 offset:19456
	ds_read_b128 v[210:213], v190 offset:20480
	ds_read_b128 v[214:217], v190 offset:21504
	ds_read_b128 v[218:221], v190 offset:22528
	ds_read_b128 v[222:225], v190 offset:23552
	global_load_lds_dwordx4 v[184:185], off
	s_add_i32 m0, s48, 0x2000
	s_add_u32 s48, s52, 0x80000
	v_lshl_add_u64 v[226:227], s[52:53], 0, v[158:159]
	s_addc_u32 s49, s53, 0
	s_add_i32 s58, s72, s3
	global_load_lds_dwordx4 v[226:227], off
	v_lshl_add_u64 v[228:229], s[48:49], 0, v[154:155]
	s_mov_b32 m0, s58
	v_lshl_add_u64 v[230:231], s[54:55], 0, v[156:157]
	global_load_lds_dwordx4 v[228:229], off
	v_lshl_add_u64 v[228:229], s[48:49], 0, v[158:159]
	s_add_i32 m0, s58, 0x2000
	s_nop 0
	global_load_lds_dwordx4 v[228:229], off
	v_lshl_add_u64 v[228:229], s[54:55], 0, v[152:153]
	s_mov_b32 m0, s60
	s_nop 0
	global_load_lds_dwordx4 v[228:229], off
	s_mov_b32 m0, s61
	s_nop 0
	global_load_lds_dwordx4 v[230:231], off
	s_waitcnt vmcnt(8)
	s_waitcnt lgkmcnt(0)
	s_waitcnt lgkmcnt(0)
	s_barrier
	s_setprio 1
	v_mfma_f32_16x16x32_bf16 v[60:63], v[128:131], v[194:197], 0
	v_mfma_f32_16x16x32_bf16 v[56:59], v[136:139], v[194:197], 0
	v_mfma_f32_16x16x32_bf16 v[44:47], v[128:131], v[202:205], 0
	v_mfma_f32_16x16x32_bf16 v[40:43], v[136:139], v[202:205], 0
	v_mfma_f32_16x16x32_bf16 v[28:31], v[128:131], v[210:213], 0
	v_mfma_f32_16x16x32_bf16 v[24:27], v[136:139], v[210:213], 0
	v_mfma_f32_16x16x32_bf16 v[12:15], v[128:131], v[218:221], 0
	v_mfma_f32_16x16x32_bf16 v[8:11], v[136:139], v[218:221], 0
	v_mfma_f32_16x16x32_bf16 v[60:63], v[132:135], v[198:201], v[60:63]
	v_mfma_f32_16x16x32_bf16 v[56:59], v[140:143], v[198:201], v[56:59]
	v_mfma_f32_16x16x32_bf16 v[44:47], v[132:135], v[206:209], v[44:47]
	v_mfma_f32_16x16x32_bf16 v[40:43], v[140:143], v[206:209], v[40:43]
	v_mfma_f32_16x16x32_bf16 v[28:31], v[132:135], v[214:217], v[28:31]
	v_mfma_f32_16x16x32_bf16 v[24:27], v[140:143], v[214:217], v[24:27]
	v_mfma_f32_16x16x32_bf16 v[12:15], v[132:135], v[222:225], v[12:15]
	v_mfma_f32_16x16x32_bf16 v[8:11], v[140:143], v[222:225], v[8:11]
	s_setprio 0
	s_setprio 1
	v_mfma_f32_16x16x32_bf16 v[52:55], v[144:147], v[194:197], 0
	v_mfma_f32_16x16x32_bf16 v[48:51], v[176:179], v[194:197], 0
	v_mfma_f32_16x16x32_bf16 v[36:39], v[144:147], v[202:205], 0
	v_mfma_f32_16x16x32_bf16 v[32:35], v[176:179], v[202:205], 0
	v_mfma_f32_16x16x32_bf16 v[20:23], v[144:147], v[210:213], 0
	v_mfma_f32_16x16x32_bf16 v[16:19], v[176:179], v[210:213], 0
	v_mfma_f32_16x16x32_bf16 v[4:7], v[144:147], v[218:221], 0
	v_mfma_f32_16x16x32_bf16 v[0:3], v[176:179], v[218:221], 0
	v_mfma_f32_16x16x32_bf16 v[52:55], v[148:151], v[198:201], v[52:55]
	v_mfma_f32_16x16x32_bf16 v[48:51], v[180:183], v[198:201], v[48:51]
	v_mfma_f32_16x16x32_bf16 v[36:39], v[148:151], v[206:209], v[36:39]
	v_mfma_f32_16x16x32_bf16 v[32:35], v[180:183], v[206:209], v[32:35]
	v_mfma_f32_16x16x32_bf16 v[20:23], v[148:151], v[214:217], v[20:23]
	v_mfma_f32_16x16x32_bf16 v[16:19], v[180:183], v[214:217], v[16:19]
	v_mfma_f32_16x16x32_bf16 v[4:7], v[148:151], v[222:225], v[4:7]
	v_mfma_f32_16x16x32_bf16 v[0:3], v[180:183], v[222:225], v[0:3]
	s_setprio 0
	s_barrier
	s_branch .Lpeel_mid_p1
.LBB0_146:
	ds_read_b128 v[128:131], v188
	ds_read_b128 v[132:135], v188 offset:1024
	ds_read_b128 v[136:139], v188 offset:2048
	ds_read_b128 v[140:143], v188 offset:3072
	ds_read_b128 v[144:147], v189
	ds_read_b128 v[148:151], v189 offset:1024
	ds_read_b128 v[176:179], v189 offset:2048
	ds_read_b128 v[180:183], v189 offset:3072
	s_add_u32 s50, s48, 0x100
	s_addc_u32 s51, s49, 0
	s_cmp_eq_u32 s57, 28
	s_cselect_b32 s55, s21, s51
	s_cselect_b32 s54, s20, s50
	s_cselect_b32 s53, s23, s56
	s_cselect_b32 s52, s22, s27
	v_lshl_add_u64 v[184:185], s[48:49], 0, v[170:171]
	s_add_i32 m0, s60, 0xc000
	ds_read_b128 v[194:197], v190
	ds_read_b128 v[198:201], v190 offset:1024
	ds_read_b128 v[202:205], v190 offset:2048
	ds_read_b128 v[206:209], v190 offset:3072
	ds_read_b128 v[210:213], v190 offset:4096
	ds_read_b128 v[214:217], v190 offset:5120
	ds_read_b128 v[218:221], v190 offset:6144
	ds_read_b128 v[222:225], v190 offset:7168
	global_load_lds_dwordx4 v[184:185], off
	v_lshl_add_u64 v[184:185], s[48:49], 0, v[172:173]
	s_add_i32 m0, s60, 0xe000
	s_nop 0
	global_load_lds_dwordx4 v[184:185], off
	s_waitcnt vmcnt(8)
	s_waitcnt lgkmcnt(0)
	s_waitcnt lgkmcnt(0)
	s_barrier
	s_setprio 1
	v_mfma_f32_16x16x32_bf16 v[120:123], v[128:131], v[194:197], v[120:123]
	v_mfma_f32_16x16x32_bf16 v[124:127], v[136:139], v[194:197], v[124:127]
	v_mfma_f32_16x16x32_bf16 v[108:111], v[128:131], v[202:205], v[108:111]
	v_mfma_f32_16x16x32_bf16 v[104:107], v[136:139], v[202:205], v[104:107]
	v_mfma_f32_16x16x32_bf16 v[92:95], v[128:131], v[210:213], v[92:95]
	v_mfma_f32_16x16x32_bf16 v[88:91], v[136:139], v[210:213], v[88:91]
	v_mfma_f32_16x16x32_bf16 v[76:79], v[128:131], v[218:221], v[76:79]
	v_mfma_f32_16x16x32_bf16 v[72:75], v[136:139], v[218:221], v[72:75]
	v_mfma_f32_16x16x32_bf16 v[120:123], v[132:135], v[198:201], v[120:123]
	v_mfma_f32_16x16x32_bf16 v[124:127], v[140:143], v[198:201], v[124:127]
	v_mfma_f32_16x16x32_bf16 v[108:111], v[132:135], v[206:209], v[108:111]
	v_mfma_f32_16x16x32_bf16 v[104:107], v[140:143], v[206:209], v[104:107]
	v_mfma_f32_16x16x32_bf16 v[92:95], v[132:135], v[214:217], v[92:95]
	v_mfma_f32_16x16x32_bf16 v[88:91], v[140:143], v[214:217], v[88:91]
	v_mfma_f32_16x16x32_bf16 v[76:79], v[132:135], v[222:225], v[76:79]
	v_mfma_f32_16x16x32_bf16 v[72:75], v[140:143], v[222:225], v[72:75]
	s_setprio 0
	s_setprio 1
	v_mfma_f32_16x16x32_bf16 v[112:115], v[144:147], v[194:197], v[112:115]
	v_mfma_f32_16x16x32_bf16 v[116:119], v[176:179], v[194:197], v[116:119]
	v_mfma_f32_16x16x32_bf16 v[100:103], v[144:147], v[202:205], v[100:103]
	v_mfma_f32_16x16x32_bf16 v[96:99], v[176:179], v[202:205], v[96:99]
	v_mfma_f32_16x16x32_bf16 v[84:87], v[144:147], v[210:213], v[84:87]
	v_mfma_f32_16x16x32_bf16 v[80:83], v[176:179], v[210:213], v[80:83]
	v_mfma_f32_16x16x32_bf16 v[68:71], v[144:147], v[218:221], v[68:71]
	v_mfma_f32_16x16x32_bf16 v[64:67], v[176:179], v[218:221], v[64:67]
	v_mfma_f32_16x16x32_bf16 v[112:115], v[148:151], v[198:201], v[112:115]
	v_mfma_f32_16x16x32_bf16 v[116:119], v[180:183], v[198:201], v[116:119]
	v_mfma_f32_16x16x32_bf16 v[100:103], v[148:151], v[206:209], v[100:103]
	v_mfma_f32_16x16x32_bf16 v[96:99], v[180:183], v[206:209], v[96:99]
	v_mfma_f32_16x16x32_bf16 v[84:87], v[148:151], v[214:217], v[84:87]
	v_mfma_f32_16x16x32_bf16 v[80:83], v[180:183], v[214:217], v[80:83]
	v_mfma_f32_16x16x32_bf16 v[68:71], v[148:151], v[222:225], v[68:71]
	v_mfma_f32_16x16x32_bf16 v[64:67], v[180:183], v[222:225], v[64:67]
	s_setprio 0
	s_barrier
	s_add_i32 s48, s71, s3
	v_lshl_add_u64 v[184:185], s[52:53], 0, v[154:155]
	s_mov_b32 m0, s48
	ds_read_b128 v[194:197], v190 offset:16384
	ds_read_b128 v[198:201], v190 offset:17408
	ds_read_b128 v[202:205], v190 offset:18432
	ds_read_b128 v[206:209], v190 offset:19456
	ds_read_b128 v[210:213], v190 offset:20480
	ds_read_b128 v[214:217], v190 offset:21504
	ds_read_b128 v[218:221], v190 offset:22528
	ds_read_b128 v[222:225], v190 offset:23552
	global_load_lds_dwordx4 v[184:185], off
	s_add_i32 m0, s48, 0x2000
	s_add_u32 s48, s52, 0x80000
	v_lshl_add_u64 v[226:227], s[52:53], 0, v[158:159]
	s_addc_u32 s49, s53, 0
	s_add_i32 s58, s72, s3
	global_load_lds_dwordx4 v[226:227], off
	v_lshl_add_u64 v[228:229], s[48:49], 0, v[154:155]
	s_mov_b32 m0, s58
	v_lshl_add_u64 v[230:231], s[54:55], 0, v[156:157]
	global_load_lds_dwordx4 v[228:229], off
	v_lshl_add_u64 v[228:229], s[48:49], 0, v[158:159]
	s_add_i32 m0, s58, 0x2000
	s_nop 0
	global_load_lds_dwordx4 v[228:229], off
	v_lshl_add_u64 v[228:229], s[54:55], 0, v[152:153]
	s_mov_b32 m0, s60
	s_nop 0
	global_load_lds_dwordx4 v[228:229], off
	s_mov_b32 m0, s61
	s_nop 0
	global_load_lds_dwordx4 v[230:231], off
	s_waitcnt vmcnt(8)
	s_waitcnt lgkmcnt(0)
	s_waitcnt lgkmcnt(0)
	s_barrier
	s_setprio 1
	v_mfma_f32_16x16x32_bf16 v[60:63], v[128:131], v[194:197], v[60:63]
	v_mfma_f32_16x16x32_bf16 v[56:59], v[136:139], v[194:197], v[56:59]
	v_mfma_f32_16x16x32_bf16 v[44:47], v[128:131], v[202:205], v[44:47]
	v_mfma_f32_16x16x32_bf16 v[40:43], v[136:139], v[202:205], v[40:43]
	v_mfma_f32_16x16x32_bf16 v[28:31], v[128:131], v[210:213], v[28:31]
	v_mfma_f32_16x16x32_bf16 v[24:27], v[136:139], v[210:213], v[24:27]
	v_mfma_f32_16x16x32_bf16 v[12:15], v[128:131], v[218:221], v[12:15]
	v_mfma_f32_16x16x32_bf16 v[8:11], v[136:139], v[218:221], v[8:11]
	v_mfma_f32_16x16x32_bf16 v[60:63], v[132:135], v[198:201], v[60:63]
	v_mfma_f32_16x16x32_bf16 v[56:59], v[140:143], v[198:201], v[56:59]
	v_mfma_f32_16x16x32_bf16 v[44:47], v[132:135], v[206:209], v[44:47]
	v_mfma_f32_16x16x32_bf16 v[40:43], v[140:143], v[206:209], v[40:43]
	v_mfma_f32_16x16x32_bf16 v[28:31], v[132:135], v[214:217], v[28:31]
	v_mfma_f32_16x16x32_bf16 v[24:27], v[140:143], v[214:217], v[24:27]
	v_mfma_f32_16x16x32_bf16 v[12:15], v[132:135], v[222:225], v[12:15]
	v_mfma_f32_16x16x32_bf16 v[8:11], v[140:143], v[222:225], v[8:11]
	s_setprio 0
	s_setprio 1
	v_mfma_f32_16x16x32_bf16 v[52:55], v[144:147], v[194:197], v[52:55]
	v_mfma_f32_16x16x32_bf16 v[48:51], v[176:179], v[194:197], v[48:51]
	v_mfma_f32_16x16x32_bf16 v[36:39], v[144:147], v[202:205], v[36:39]
	v_mfma_f32_16x16x32_bf16 v[32:35], v[176:179], v[202:205], v[32:35]
	v_mfma_f32_16x16x32_bf16 v[20:23], v[144:147], v[210:213], v[20:23]
	v_mfma_f32_16x16x32_bf16 v[16:19], v[176:179], v[210:213], v[16:19]
	v_mfma_f32_16x16x32_bf16 v[4:7], v[144:147], v[218:221], v[4:7]
	v_mfma_f32_16x16x32_bf16 v[0:3], v[176:179], v[218:221], v[0:3]
	v_mfma_f32_16x16x32_bf16 v[52:55], v[148:151], v[198:201], v[52:55]
	v_mfma_f32_16x16x32_bf16 v[48:51], v[180:183], v[198:201], v[48:51]
	v_mfma_f32_16x16x32_bf16 v[36:39], v[148:151], v[206:209], v[36:39]
	v_mfma_f32_16x16x32_bf16 v[32:35], v[180:183], v[206:209], v[32:35]
	v_mfma_f32_16x16x32_bf16 v[20:23], v[148:151], v[214:217], v[20:23]
	v_mfma_f32_16x16x32_bf16 v[16:19], v[180:183], v[214:217], v[16:19]
	v_mfma_f32_16x16x32_bf16 v[4:7], v[148:151], v[222:225], v[4:7]
	v_mfma_f32_16x16x32_bf16 v[0:3], v[180:183], v[222:225], v[0:3]
	s_setprio 0
	s_barrier
.Lpeel_mid_p1:
	s_add_i32 s58, 0, 0x18000
	s_add_i32 s59, 0, 0x1c000
	v_add_u32_e32 v140, s58, v186
	v_add_u32_e32 v160, s59, v186
	ds_read_b128 v[128:131], v140
	ds_read_b128 v[132:135], v140 offset:1024
	ds_read_b128 v[136:139], v140 offset:2048
	ds_read_b128 v[140:143], v140 offset:3072
	ds_read_b128 v[144:147], v160
	ds_read_b128 v[148:151], v160 offset:1024
	ds_read_b128 v[176:179], v160 offset:2048
	ds_read_b128 v[180:183], v160 offset:3072
	s_add_u32 s48, s54, 0xa0000
	s_addc_u32 s49, s55, 0
	s_mov_b32 m0, s62
	v_lshl_add_u64 v[232:233], s[48:49], 0, v[152:153]
	ds_read_b128 v[194:197], v190 offset:32768
	ds_read_b128 v[198:201], v190 offset:33792
	ds_read_b128 v[202:205], v190 offset:34816
	ds_read_b128 v[206:209], v190 offset:35840
	ds_read_b128 v[210:213], v190 offset:36864
	ds_read_b128 v[214:217], v190 offset:37888
	ds_read_b128 v[218:221], v190 offset:38912
	ds_read_b128 v[222:225], v190 offset:39936
	global_load_lds_dwordx4 v[232:233], off
	v_lshl_add_u64 v[232:233], s[48:49], 0, v[156:157]
	s_mov_b32 m0, s63
	s_nop 0
	global_load_lds_dwordx4 v[232:233], off
	s_waitcnt vmcnt(8)
	s_waitcnt lgkmcnt(0)
	s_waitcnt lgkmcnt(0)
	s_barrier
	s_setprio 1
	v_mfma_f32_16x16x32_bf16 v[120:123], v[128:131], v[194:197], v[120:123]
	v_mfma_f32_16x16x32_bf16 v[124:127], v[136:139], v[194:197], v[124:127]
	v_mfma_f32_16x16x32_bf16 v[108:111], v[128:131], v[202:205], v[108:111]
	v_mfma_f32_16x16x32_bf16 v[104:107], v[136:139], v[202:205], v[104:107]
	v_mfma_f32_16x16x32_bf16 v[92:95], v[128:131], v[210:213], v[92:95]
	v_mfma_f32_16x16x32_bf16 v[88:91], v[136:139], v[210:213], v[88:91]
	v_mfma_f32_16x16x32_bf16 v[76:79], v[128:131], v[218:221], v[76:79]
	v_mfma_f32_16x16x32_bf16 v[72:75], v[136:139], v[218:221], v[72:75]
	v_mfma_f32_16x16x32_bf16 v[120:123], v[132:135], v[198:201], v[120:123]
	v_mfma_f32_16x16x32_bf16 v[124:127], v[140:143], v[198:201], v[124:127]
	v_mfma_f32_16x16x32_bf16 v[108:111], v[132:135], v[206:209], v[108:111]
	v_mfma_f32_16x16x32_bf16 v[104:107], v[140:143], v[206:209], v[104:107]
	v_mfma_f32_16x16x32_bf16 v[92:95], v[132:135], v[214:217], v[92:95]
	v_mfma_f32_16x16x32_bf16 v[88:91], v[140:143], v[214:217], v[88:91]
	v_mfma_f32_16x16x32_bf16 v[76:79], v[132:135], v[222:225], v[76:79]
	v_mfma_f32_16x16x32_bf16 v[72:75], v[140:143], v[222:225], v[72:75]
	s_setprio 0
	s_setprio 1
	v_mfma_f32_16x16x32_bf16 v[112:115], v[144:147], v[194:197], v[112:115]
	v_mfma_f32_16x16x32_bf16 v[116:119], v[176:179], v[194:197], v[116:119]
	v_mfma_f32_16x16x32_bf16 v[100:103], v[144:147], v[202:205], v[100:103]
	v_mfma_f32_16x16x32_bf16 v[96:99], v[176:179], v[202:205], v[96:99]
	v_mfma_f32_16x16x32_bf16 v[84:87], v[144:147], v[210:213], v[84:87]
	v_mfma_f32_16x16x32_bf16 v[80:83], v[176:179], v[210:213], v[80:83]
	v_mfma_f32_16x16x32_bf16 v[68:71], v[144:147], v[218:221], v[68:71]
	v_mfma_f32_16x16x32_bf16 v[64:67], v[176:179], v[218:221], v[64:67]
	v_mfma_f32_16x16x32_bf16 v[112:115], v[148:151], v[198:201], v[112:115]
	v_mfma_f32_16x16x32_bf16 v[116:119], v[180:183], v[198:201], v[116:119]
	v_mfma_f32_16x16x32_bf16 v[100:103], v[148:151], v[206:209], v[100:103]
	v_mfma_f32_16x16x32_bf16 v[96:99], v[180:183], v[206:209], v[96:99]
	v_mfma_f32_16x16x32_bf16 v[84:87], v[148:151], v[214:217], v[84:87]
	v_mfma_f32_16x16x32_bf16 v[80:83], v[180:183], v[214:217], v[80:83]
	v_mfma_f32_16x16x32_bf16 v[68:71], v[148:151], v[222:225], v[68:71]
	v_mfma_f32_16x16x32_bf16 v[64:67], v[180:183], v[222:225], v[64:67]
	s_setprio 0
	s_barrier
	s_add_i32 s48, s58, s3
	v_lshl_add_u64 v[184:185], v[184:185], 0, s[14:15]
	s_mov_b32 m0, s48
	ds_read_b128 v[194:197], v190 offset:49152
	ds_read_b128 v[198:201], v190 offset:50176
	ds_read_b128 v[202:205], v190 offset:51200
	ds_read_b128 v[206:209], v190 offset:52224
	ds_read_b128 v[210:213], v190 offset:53248
	ds_read_b128 v[214:217], v190 offset:54272
	ds_read_b128 v[218:221], v190 offset:55296
	ds_read_b128 v[222:225], v190 offset:56320
	global_load_lds_dwordx4 v[184:185], off
	s_add_i32 m0, s48, 0x2000
	s_add_u32 s48, s52, 0x80080
	v_lshl_add_u64 v[184:185], v[226:227], 0, s[14:15]
	s_addc_u32 s49, s53, 0
	s_add_i32 s52, s59, s3
	global_load_lds_dwordx4 v[184:185], off
	v_lshl_add_u64 v[184:185], s[48:49], 0, v[154:155]
	s_mov_b32 m0, s52
	s_nop 0
	global_load_lds_dwordx4 v[184:185], off
	v_lshl_add_u64 v[184:185], s[48:49], 0, v[158:159]
	s_add_i32 m0, s52, 0x2000
	s_nop 0
	global_load_lds_dwordx4 v[184:185], off
	v_lshl_add_u64 v[184:185], v[228:229], 0, s[14:15]
	s_mov_b32 m0, s66
	s_nop 0
	global_load_lds_dwordx4 v[184:185], off
	v_lshl_add_u64 v[184:185], v[230:231], 0, s[14:15]
	s_mov_b32 m0, s67
	s_nop 0
	global_load_lds_dwordx4 v[184:185], off
	s_waitcnt vmcnt(8)
	s_waitcnt lgkmcnt(0)
	s_waitcnt lgkmcnt(0)
	s_barrier
	s_setprio 1
	v_mfma_f32_16x16x32_bf16 v[60:63], v[128:131], v[194:197], v[60:63]
	v_mfma_f32_16x16x32_bf16 v[56:59], v[136:139], v[194:197], v[56:59]
	v_mfma_f32_16x16x32_bf16 v[44:47], v[128:131], v[202:205], v[44:47]
	v_mfma_f32_16x16x32_bf16 v[40:43], v[136:139], v[202:205], v[40:43]
	v_mfma_f32_16x16x32_bf16 v[28:31], v[128:131], v[210:213], v[28:31]
	v_mfma_f32_16x16x32_bf16 v[24:27], v[136:139], v[210:213], v[24:27]
	v_mfma_f32_16x16x32_bf16 v[12:15], v[128:131], v[218:221], v[12:15]
	v_mfma_f32_16x16x32_bf16 v[8:11], v[136:139], v[218:221], v[8:11]
	v_mfma_f32_16x16x32_bf16 v[60:63], v[132:135], v[198:201], v[60:63]
	v_mfma_f32_16x16x32_bf16 v[56:59], v[140:143], v[198:201], v[56:59]
	v_mfma_f32_16x16x32_bf16 v[44:47], v[132:135], v[206:209], v[44:47]
	v_mfma_f32_16x16x32_bf16 v[40:43], v[140:143], v[206:209], v[40:43]
	v_mfma_f32_16x16x32_bf16 v[28:31], v[132:135], v[214:217], v[28:31]
	v_mfma_f32_16x16x32_bf16 v[24:27], v[140:143], v[214:217], v[24:27]
	v_mfma_f32_16x16x32_bf16 v[12:15], v[132:135], v[222:225], v[12:15]
	v_mfma_f32_16x16x32_bf16 v[8:11], v[140:143], v[222:225], v[8:11]
	s_setprio 0
	s_setprio 1
	v_mfma_f32_16x16x32_bf16 v[52:55], v[144:147], v[194:197], v[52:55]
	v_mfma_f32_16x16x32_bf16 v[48:51], v[176:179], v[194:197], v[48:51]
	v_mfma_f32_16x16x32_bf16 v[36:39], v[144:147], v[202:205], v[36:39]
	v_mfma_f32_16x16x32_bf16 v[32:35], v[176:179], v[202:205], v[32:35]
	v_mfma_f32_16x16x32_bf16 v[20:23], v[144:147], v[210:213], v[20:23]
	v_mfma_f32_16x16x32_bf16 v[16:19], v[176:179], v[210:213], v[16:19]
	v_mfma_f32_16x16x32_bf16 v[4:7], v[144:147], v[218:221], v[4:7]
	v_mfma_f32_16x16x32_bf16 v[0:3], v[176:179], v[218:221], v[0:3]
	v_mfma_f32_16x16x32_bf16 v[52:55], v[148:151], v[198:201], v[52:55]
	v_mfma_f32_16x16x32_bf16 v[48:51], v[180:183], v[198:201], v[48:51]
	v_mfma_f32_16x16x32_bf16 v[36:39], v[148:151], v[206:209], v[36:39]
	v_mfma_f32_16x16x32_bf16 v[32:35], v[180:183], v[206:209], v[32:35]
	v_mfma_f32_16x16x32_bf16 v[20:23], v[148:151], v[214:217], v[20:23]
	v_mfma_f32_16x16x32_bf16 v[16:19], v[180:183], v[214:217], v[16:19]
	v_mfma_f32_16x16x32_bf16 v[4:7], v[148:151], v[222:225], v[4:7]
	v_mfma_f32_16x16x32_bf16 v[0:3], v[180:183], v[222:225], v[0:3]
	s_setprio 0
	s_barrier
	s_add_i32 s57, s57, 2
	s_add_u32 s27, s27, 0x100
	s_addc_u32 s56, s56, 0
	s_cmp_gt_u32 s57, 29
	s_mov_b64 s[48:49], s[50:51]
	s_cbranch_scc0 .LBB0_146
	s_and_b64 vcc, exec, s[18:19]
	s_cbranch_vccz .LBB0_149
	s_barrier

.LBB0_250:
	ds_read_b128 v[148:151], v142
	ds_read_b128 v[152:155], v142 offset:1024
	ds_read_b128 v[156:159], v142 offset:2048
	ds_read_b128 v[160:163], v142 offset:3072
	ds_read_b128 v[164:167], v143
	ds_read_b128 v[168:171], v143 offset:1024
	ds_read_b128 v[176:179], v143 offset:2048
	ds_read_b128 v[180:183], v143 offset:3072
	s_add_i32 s20, s18, 0xf4f60080
	s_cmp_lg_u32 s52, 28
	s_cselect_b32 s20, s20, 0
	s_add_u32 s22, s2, s20
	s_addc_u32 s23, s3, 0
	s_add_u32 s20, s12, s20
	s_addc_u32 s21, s13, 0
	s_mov_b32 m0, s53
	v_lshl_add_u64 v[172:173], v[138:139], 0, s[18:19]
	ds_read_b128 v[188:191], v144
	ds_read_b128 v[192:195], v144 offset:1024
	ds_read_b128 v[196:199], v144 offset:2048
	ds_read_b128 v[200:203], v144 offset:3072
	ds_read_b128 v[204:207], v144 offset:4096
	ds_read_b128 v[208:211], v144 offset:5120
	ds_read_b128 v[212:215], v144 offset:6144
	ds_read_b128 v[216:219], v144 offset:7168
	global_load_lds_dwordx4 v[172:173], off
	v_lshl_add_u64 v[172:173], v[140:141], 0, s[18:19]
	s_mov_b32 m0, s54
	s_nop 0
	global_load_lds_dwordx4 v[172:173], off
	s_waitcnt vmcnt(8)
	s_waitcnt lgkmcnt(0)
	s_waitcnt lgkmcnt(0)
	s_barrier
	s_setprio 1
	v_mfma_f32_16x16x32_bf16 v[124:127], v[148:151], v[188:191], v[124:127]
	v_mfma_f32_16x16x32_bf16 v[120:123], v[156:159], v[188:191], v[120:123]
	v_mfma_f32_16x16x32_bf16 v[116:119], v[148:151], v[196:199], v[116:119]
	v_mfma_f32_16x16x32_bf16 v[112:115], v[156:159], v[196:199], v[112:115]
	v_mfma_f32_16x16x32_bf16 v[100:103], v[148:151], v[204:207], v[100:103]
	v_mfma_f32_16x16x32_bf16 v[96:99], v[156:159], v[204:207], v[96:99]
	v_mfma_f32_16x16x32_bf16 v[84:87], v[148:151], v[212:215], v[84:87]
	v_mfma_f32_16x16x32_bf16 v[80:83], v[156:159], v[212:215], v[80:83]
	v_mfma_f32_16x16x32_bf16 v[124:127], v[152:155], v[192:195], v[124:127]
	v_mfma_f32_16x16x32_bf16 v[120:123], v[160:163], v[192:195], v[120:123]
	v_mfma_f32_16x16x32_bf16 v[116:119], v[152:155], v[200:203], v[116:119]
	v_mfma_f32_16x16x32_bf16 v[112:115], v[160:163], v[200:203], v[112:115]
	v_mfma_f32_16x16x32_bf16 v[100:103], v[152:155], v[208:211], v[100:103]
	v_mfma_f32_16x16x32_bf16 v[96:99], v[160:163], v[208:211], v[96:99]
	v_mfma_f32_16x16x32_bf16 v[84:87], v[152:155], v[216:219], v[84:87]
	v_mfma_f32_16x16x32_bf16 v[80:83], v[160:163], v[216:219], v[80:83]
	s_setprio 0
	s_setprio 1
	v_mfma_f32_16x16x32_bf16 v[108:111], v[164:167], v[188:191], v[108:111]
	v_mfma_f32_16x16x32_bf16 v[104:107], v[176:179], v[188:191], v[104:107]
	v_mfma_f32_16x16x32_bf16 v[92:95], v[164:167], v[196:199], v[92:95]
	v_mfma_f32_16x16x32_bf16 v[88:91], v[176:179], v[196:199], v[88:91]
	v_mfma_f32_16x16x32_bf16 v[76:79], v[164:167], v[204:207], v[76:79]
	v_mfma_f32_16x16x32_bf16 v[72:75], v[176:179], v[204:207], v[72:75]
	v_mfma_f32_16x16x32_bf16 v[68:71], v[164:167], v[212:215], v[68:71]
	v_mfma_f32_16x16x32_bf16 v[64:67], v[176:179], v[212:215], v[64:67]
	v_mfma_f32_16x16x32_bf16 v[108:111], v[168:171], v[192:195], v[108:111]
	v_mfma_f32_16x16x32_bf16 v[104:107], v[180:183], v[192:195], v[104:107]
	v_mfma_f32_16x16x32_bf16 v[92:95], v[168:171], v[200:203], v[92:95]
	v_mfma_f32_16x16x32_bf16 v[88:91], v[180:183], v[200:203], v[88:91]
	v_mfma_f32_16x16x32_bf16 v[76:79], v[168:171], v[208:211], v[76:79]
	v_mfma_f32_16x16x32_bf16 v[72:75], v[180:183], v[208:211], v[72:75]
	v_mfma_f32_16x16x32_bf16 v[68:71], v[168:171], v[216:219], v[68:71]
	v_mfma_f32_16x16x32_bf16 v[64:67], v[180:183], v[216:219], v[64:67]
	s_setprio 0
	s_barrier
	s_mov_b32 m0, s55
	v_lshl_add_u64 v[172:173], s[20:21], 0, v[132:133]
	s_add_u32 s64, s20, 0x80000
	ds_read_b128 v[188:191], v144 offset:16384
	ds_read_b128 v[192:195], v144 offset:17408
	ds_read_b128 v[196:199], v144 offset:18432
	ds_read_b128 v[200:203], v144 offset:19456
	ds_read_b128 v[204:207], v144 offset:20480
	ds_read_b128 v[208:211], v144 offset:21504
	ds_read_b128 v[212:215], v144 offset:22528
	ds_read_b128 v[216:219], v144 offset:23552
	global_load_lds_dwordx4 v[172:173], off
	v_lshl_add_u64 v[184:185], s[20:21], 0, v[128:129]
	s_mov_b32 m0, s56
	s_addc_u32 s65, s21, 0
	global_load_lds_dwordx4 v[184:185], off
	v_lshl_add_u64 v[220:221], s[64:65], 0, v[132:133]
	s_mov_b32 m0, s57
	v_lshl_add_u64 v[222:223], s[22:23], 0, v[130:131]
	global_load_lds_dwordx4 v[220:221], off
	v_lshl_add_u64 v[220:221], s[64:65], 0, v[128:129]
	s_mov_b32 m0, s58
	s_nop 0
	global_load_lds_dwordx4 v[220:221], off
	v_lshl_add_u64 v[220:221], s[22:23], 0, v[134:135]
	s_mov_b32 m0, s1
	s_nop 0
	global_load_lds_dwordx4 v[220:221], off
	s_mov_b32 m0, s26
	s_nop 0
	global_load_lds_dwordx4 v[222:223], off
	s_waitcnt vmcnt(8)
	s_waitcnt lgkmcnt(0)
	s_waitcnt lgkmcnt(0)
	s_barrier
	s_setprio 1
	v_mfma_f32_16x16x32_bf16 v[60:63], v[148:151], v[188:191], v[60:63]
	v_mfma_f32_16x16x32_bf16 v[56:59], v[156:159], v[188:191], v[56:59]
	v_mfma_f32_16x16x32_bf16 v[52:55], v[148:151], v[196:199], v[52:55]
	v_mfma_f32_16x16x32_bf16 v[48:51], v[156:159], v[196:199], v[48:51]
	v_mfma_f32_16x16x32_bf16 v[36:39], v[148:151], v[204:207], v[36:39]
	v_mfma_f32_16x16x32_bf16 v[32:35], v[156:159], v[204:207], v[32:35]
	v_mfma_f32_16x16x32_bf16 v[20:23], v[148:151], v[212:215], v[20:23]
	v_mfma_f32_16x16x32_bf16 v[16:19], v[156:159], v[212:215], v[16:19]
	v_mfma_f32_16x16x32_bf16 v[60:63], v[152:155], v[192:195], v[60:63]
	v_mfma_f32_16x16x32_bf16 v[56:59], v[160:163], v[192:195], v[56:59]
	v_mfma_f32_16x16x32_bf16 v[52:55], v[152:155], v[200:203], v[52:55]
	v_mfma_f32_16x16x32_bf16 v[48:51], v[160:163], v[200:203], v[48:51]
	v_mfma_f32_16x16x32_bf16 v[36:39], v[152:155], v[208:211], v[36:39]
	v_mfma_f32_16x16x32_bf16 v[32:35], v[160:163], v[208:211], v[32:35]
	v_mfma_f32_16x16x32_bf16 v[20:23], v[152:155], v[216:219], v[20:23]
	v_mfma_f32_16x16x32_bf16 v[16:19], v[160:163], v[216:219], v[16:19]
	s_setprio 0
	s_setprio 1
	v_mfma_f32_16x16x32_bf16 v[44:47], v[164:167], v[188:191], v[44:47]
	v_mfma_f32_16x16x32_bf16 v[40:43], v[176:179], v[188:191], v[40:43]
	v_mfma_f32_16x16x32_bf16 v[28:31], v[164:167], v[196:199], v[28:31]
	v_mfma_f32_16x16x32_bf16 v[24:27], v[176:179], v[196:199], v[24:27]
	v_mfma_f32_16x16x32_bf16 v[12:15], v[164:167], v[204:207], v[12:15]
	v_mfma_f32_16x16x32_bf16 v[8:11], v[176:179], v[204:207], v[8:11]
	v_mfma_f32_16x16x32_bf16 v[4:7], v[164:167], v[212:215], v[4:7]
	v_mfma_f32_16x16x32_bf16 v[0:3], v[176:179], v[212:215], v[0:3]
	v_mfma_f32_16x16x32_bf16 v[44:47], v[168:171], v[192:195], v[44:47]
	v_mfma_f32_16x16x32_bf16 v[40:43], v[180:183], v[192:195], v[40:43]
	v_mfma_f32_16x16x32_bf16 v[28:31], v[168:171], v[200:203], v[28:31]
	v_mfma_f32_16x16x32_bf16 v[24:27], v[180:183], v[200:203], v[24:27]
	v_mfma_f32_16x16x32_bf16 v[12:15], v[168:171], v[208:211], v[12:15]
	v_mfma_f32_16x16x32_bf16 v[8:11], v[180:183], v[208:211], v[8:11]
	v_mfma_f32_16x16x32_bf16 v[4:7], v[168:171], v[216:219], v[4:7]
	v_mfma_f32_16x16x32_bf16 v[0:3], v[180:183], v[216:219], v[0:3]
	s_setprio 0
	s_barrier
	ds_read_b128 v[148:151], v145
	ds_read_b128 v[152:155], v145 offset:1024
	ds_read_b128 v[156:159], v145 offset:2048
	ds_read_b128 v[160:163], v145 offset:3072
	ds_read_b128 v[164:167], v146
	ds_read_b128 v[168:171], v146 offset:1024
	ds_read_b128 v[176:179], v146 offset:2048
	ds_read_b128 v[180:183], v146 offset:3072
	s_add_u32 s22, s22, 0xa0000
	s_addc_u32 s23, s23, 0
	s_mov_b32 m0, s27
	v_lshl_add_u64 v[224:225], s[22:23], 0, v[134:135]
	ds_read_b128 v[188:191], v144 offset:32768
	ds_read_b128 v[192:195], v144 offset:33792
	ds_read_b128 v[196:199], v144 offset:34816
	ds_read_b128 v[200:203], v144 offset:35840
	ds_read_b128 v[204:207], v144 offset:36864
	ds_read_b128 v[208:211], v144 offset:37888
	ds_read_b128 v[212:215], v144 offset:38912
	ds_read_b128 v[216:219], v144 offset:39936
	global_load_lds_dwordx4 v[224:225], off
	v_lshl_add_u64 v[224:225], s[22:23], 0, v[130:131]
	s_mov_b32 m0, s48
	s_nop 0
	global_load_lds_dwordx4 v[224:225], off
	s_waitcnt vmcnt(8)
	s_waitcnt lgkmcnt(0)
	s_waitcnt lgkmcnt(0)
	s_barrier
	s_setprio 1
	v_mfma_f32_16x16x32_bf16 v[124:127], v[148:151], v[188:191], v[124:127]
	v_mfma_f32_16x16x32_bf16 v[120:123], v[156:159], v[188:191], v[120:123]
	v_mfma_f32_16x16x32_bf16 v[116:119], v[148:151], v[196:199], v[116:119]
	v_mfma_f32_16x16x32_bf16 v[112:115], v[156:159], v[196:199], v[112:115]
	v_mfma_f32_16x16x32_bf16 v[100:103], v[148:151], v[204:207], v[100:103]
	v_mfma_f32_16x16x32_bf16 v[96:99], v[156:159], v[204:207], v[96:99]
	v_mfma_f32_16x16x32_bf16 v[84:87], v[148:151], v[212:215], v[84:87]
	v_mfma_f32_16x16x32_bf16 v[80:83], v[156:159], v[212:215], v[80:83]
	v_mfma_f32_16x16x32_bf16 v[124:127], v[152:155], v[192:195], v[124:127]
	v_mfma_f32_16x16x32_bf16 v[120:123], v[160:163], v[192:195], v[120:123]
	v_mfma_f32_16x16x32_bf16 v[116:119], v[152:155], v[200:203], v[116:119]
	v_mfma_f32_16x16x32_bf16 v[112:115], v[160:163], v[200:203], v[112:115]
	v_mfma_f32_16x16x32_bf16 v[100:103], v[152:155], v[208:211], v[100:103]
	v_mfma_f32_16x16x32_bf16 v[96:99], v[160:163], v[208:211], v[96:99]
	v_mfma_f32_16x16x32_bf16 v[84:87], v[152:155], v[216:219], v[84:87]
	v_mfma_f32_16x16x32_bf16 v[80:83], v[160:163], v[216:219], v[80:83]
	s_setprio 0
	s_setprio 1
	v_mfma_f32_16x16x32_bf16 v[108:111], v[164:167], v[188:191], v[108:111]
	v_mfma_f32_16x16x32_bf16 v[104:107], v[176:179], v[188:191], v[104:107]
	v_mfma_f32_16x16x32_bf16 v[92:95], v[164:167], v[196:199], v[92:95]
	v_mfma_f32_16x16x32_bf16 v[88:91], v[176:179], v[196:199], v[88:91]
	v_mfma_f32_16x16x32_bf16 v[76:79], v[164:167], v[204:207], v[76:79]
	v_mfma_f32_16x16x32_bf16 v[72:75], v[176:179], v[204:207], v[72:75]
	v_mfma_f32_16x16x32_bf16 v[68:71], v[164:167], v[212:215], v[68:71]
	v_mfma_f32_16x16x32_bf16 v[64:67], v[176:179], v[212:215], v[64:67]
	v_mfma_f32_16x16x32_bf16 v[108:111], v[168:171], v[192:195], v[108:111]
	v_mfma_f32_16x16x32_bf16 v[104:107], v[180:183], v[192:195], v[104:107]
	v_mfma_f32_16x16x32_bf16 v[92:95], v[168:171], v[200:203], v[92:95]
	v_mfma_f32_16x16x32_bf16 v[88:91], v[180:183], v[200:203], v[88:91]
	v_mfma_f32_16x16x32_bf16 v[76:79], v[168:171], v[208:211], v[76:79]
	v_mfma_f32_16x16x32_bf16 v[72:75], v[180:183], v[208:211], v[72:75]
	v_mfma_f32_16x16x32_bf16 v[68:71], v[168:171], v[216:219], v[68:71]
	v_mfma_f32_16x16x32_bf16 v[64:67], v[180:183], v[216:219], v[64:67]
	s_setprio 0
	s_barrier
	s_mov_b32 m0, s59
	v_lshl_add_u64 v[172:173], v[172:173], 0, s[14:15]
	s_add_u32 s20, s20, 0x80080
	ds_read_b128 v[188:191], v144 offset:49152
	ds_read_b128 v[192:195], v144 offset:50176
	ds_read_b128 v[196:199], v144 offset:51200
	ds_read_b128 v[200:203], v144 offset:52224
	ds_read_b128 v[204:207], v144 offset:53248
	ds_read_b128 v[208:211], v144 offset:54272
	ds_read_b128 v[212:215], v144 offset:55296
	ds_read_b128 v[216:219], v144 offset:56320
	global_load_lds_dwordx4 v[172:173], off
	v_lshl_add_u64 v[172:173], v[184:185], 0, s[14:15]
	s_mov_b32 m0, s60
	s_addc_u32 s21, s21, 0
	global_load_lds_dwordx4 v[172:173], off
	v_lshl_add_u64 v[172:173], s[20:21], 0, v[132:133]
	s_mov_b32 m0, s61
	s_nop 0
	global_load_lds_dwordx4 v[172:173], off
	v_lshl_add_u64 v[172:173], s[20:21], 0, v[128:129]
	s_mov_b32 m0, s62
	s_nop 0
	global_load_lds_dwordx4 v[172:173], off
	v_lshl_add_u64 v[172:173], v[220:221], 0, s[14:15]
	s_mov_b32 m0, s50
	s_nop 0
	global_load_lds_dwordx4 v[172:173], off
	v_lshl_add_u64 v[172:173], v[222:223], 0, s[14:15]
	s_mov_b32 m0, s51
	s_nop 0
	global_load_lds_dwordx4 v[172:173], off
	s_waitcnt vmcnt(8)
	s_waitcnt lgkmcnt(0)
	s_waitcnt lgkmcnt(0)
	s_barrier
	s_setprio 1
	v_mfma_f32_16x16x32_bf16 v[60:63], v[148:151], v[188:191], v[60:63]
	v_mfma_f32_16x16x32_bf16 v[56:59], v[156:159], v[188:191], v[56:59]
	v_mfma_f32_16x16x32_bf16 v[52:55], v[148:151], v[196:199], v[52:55]
	v_mfma_f32_16x16x32_bf16 v[48:51], v[156:159], v[196:199], v[48:51]
	v_mfma_f32_16x16x32_bf16 v[36:39], v[148:151], v[204:207], v[36:39]
	v_mfma_f32_16x16x32_bf16 v[32:35], v[156:159], v[204:207], v[32:35]
	v_mfma_f32_16x16x32_bf16 v[20:23], v[148:151], v[212:215], v[20:23]
	v_mfma_f32_16x16x32_bf16 v[16:19], v[156:159], v[212:215], v[16:19]
	v_mfma_f32_16x16x32_bf16 v[60:63], v[152:155], v[192:195], v[60:63]
	v_mfma_f32_16x16x32_bf16 v[56:59], v[160:163], v[192:195], v[56:59]
	v_mfma_f32_16x16x32_bf16 v[52:55], v[152:155], v[200:203], v[52:55]
	v_mfma_f32_16x16x32_bf16 v[48:51], v[160:163], v[200:203], v[48:51]
	v_mfma_f32_16x16x32_bf16 v[36:39], v[152:155], v[208:211], v[36:39]
	v_mfma_f32_16x16x32_bf16 v[32:35], v[160:163], v[208:211], v[32:35]
	v_mfma_f32_16x16x32_bf16 v[20:23], v[152:155], v[216:219], v[20:23]
	v_mfma_f32_16x16x32_bf16 v[16:19], v[160:163], v[216:219], v[16:19]
	s_setprio 0
	s_setprio 1
	v_mfma_f32_16x16x32_bf16 v[44:47], v[164:167], v[188:191], v[44:47]
	v_mfma_f32_16x16x32_bf16 v[40:43], v[176:179], v[188:191], v[40:43]
	v_mfma_f32_16x16x32_bf16 v[28:31], v[164:167], v[196:199], v[28:31]
	v_mfma_f32_16x16x32_bf16 v[24:27], v[176:179], v[196:199], v[24:27]
	v_mfma_f32_16x16x32_bf16 v[12:15], v[164:167], v[204:207], v[12:15]
	v_mfma_f32_16x16x32_bf16 v[8:11], v[176:179], v[204:207], v[8:11]
	v_mfma_f32_16x16x32_bf16 v[4:7], v[164:167], v[212:215], v[4:7]
	v_mfma_f32_16x16x32_bf16 v[0:3], v[176:179], v[212:215], v[0:3]
	v_mfma_f32_16x16x32_bf16 v[44:47], v[168:171], v[192:195], v[44:47]
	v_mfma_f32_16x16x32_bf16 v[40:43], v[180:183], v[192:195], v[40:43]
	v_mfma_f32_16x16x32_bf16 v[28:31], v[168:171], v[200:203], v[28:31]
	v_mfma_f32_16x16x32_bf16 v[24:27], v[180:183], v[200:203], v[24:27]
	v_mfma_f32_16x16x32_bf16 v[12:15], v[168:171], v[208:211], v[12:15]
	v_mfma_f32_16x16x32_bf16 v[8:11], v[180:183], v[208:211], v[8:11]
	v_mfma_f32_16x16x32_bf16 v[4:7], v[168:171], v[216:219], v[4:7]
	v_mfma_f32_16x16x32_bf16 v[0:3], v[180:183], v[216:219], v[0:3]
	s_setprio 0
	s_barrier
	s_add_i32 s52, s52, 2
	s_add_u32 s18, s18, 0x100
	s_addc_u32 s19, s19, 0
	s_cmp_gt_u32 s52, 29
	s_cbranch_scc0 .LBB0_250
	s_cmpk_lt_u32 s24, 0x100
	s_cbranch_scc0 .LBB0_253
	s_barrier

.LBB0_596:
	s_lshl_b32 s98, s56, 3
	s_add_i32 s98, s98, s2
	s_mul_i32 s98, s98, 3
	v_lshl_add_u32 v164, s56, 8, v172
	s_cmp_eq_u32 s87, 3
	v_mad_i64_i32 v[162:163], s[56:57], v164, s77, v[156:157]
	s_cselect_b64 s[62:63], -1, 0
	s_lshl_b32 s56, s2, 8
	s_ashr_i32 s57, s56, 31
	v_lshl_add_u64 v[2:3], s[56:57], 1, v[162:163]
	s_mov_b32 s7, s3
	v_lshl_add_u64 v[2:3], v[2:3], 0, s[6:7]
	v_lshl_add_u64 v[166:167], v[2:3], 0, v[160:161]
	s_add_i32 s7, s88, -2
	s_add_u32 s89, s60, 0x100
	v_mov_b32_e32 v1, v0
	v_ashrrev_i32_e32 v165, 31, v164
	s_addc_u32 s90, s61, 0
	v_lshl_add_u64 v[168:169], s[58:59], 0, v[152:153]
	v_lshl_add_u64 v[170:171], s[58:59], 0, v[154:155]
	s_mov_b32 s64, 0
	s_mov_b64 s[60:61], 0
	s_xor_b64 s[62:63], s[62:63], -1
	v_add_u32_e32 v1, s79, v173
	s_add_i32 s2, s64, 2
	ds_read_b128 v[132:135], v1
	ds_read_b128 v[136:139], v1 offset:1024
	ds_read_b128 v[140:143], v1 offset:2048
	ds_read_b128 v[178:181], v1 offset:3072
	v_add_u32_e32 v1, s80, v173
	s_add_u32 s65, s58, s60
	ds_read_b128 v[182:185], v1
	ds_read_b128 v[188:191], v1 offset:1024
	ds_read_b128 v[192:195], v1 offset:2048
	ds_read_b128 v[196:199], v1 offset:3072
	s_addc_u32 s66, s59, s61
	s_add_u32 s65, s65, 0x100
	s_addc_u32 s66, s66, 0
	s_add_u32 s75, s89, s60
	s_addc_u32 s91, s90, s61
	s_cmp_eq_u32 s7, s64
	s_cselect_b32 s67, s51, s66
	s_cselect_b32 s66, s50, s65
	s_cselect_b32 s65, s53, s91
	s_cselect_b32 s64, s52, s75
	v_lshl_add_u64 v[2:3], v[168:169], 0, s[60:61]
	s_add_i32 m0, s69, 0xc000
	ds_read_b128 v[200:203], v174
	ds_read_b128 v[204:207], v174 offset:1024
	ds_read_b128 v[208:211], v174 offset:2048
	ds_read_b128 v[212:215], v174 offset:3072
	ds_read_b128 v[216:219], v174 offset:4096
	ds_read_b128 v[220:223], v174 offset:5120
	ds_read_b128 v[224:227], v174 offset:6144
	ds_read_b128 v[228:231], v174 offset:7168
	global_load_lds_dwordx4 v[2:3], off
	v_lshl_add_u64 v[2:3], v[170:171], 0, s[60:61]
	s_add_i32 m0, s69, 0xe000
	s_nop 0
	global_load_lds_dwordx4 v[2:3], off
	s_waitcnt vmcnt(8)
	s_waitcnt lgkmcnt(0)
	s_waitcnt lgkmcnt(0)
	s_barrier
	s_setprio 1
	v_mfma_f32_16x16x32_bf16 v[128:131], v[132:135], v[200:203], 0
	v_mfma_f32_16x16x32_bf16 v[124:127], v[140:143], v[200:203], 0
	v_mfma_f32_16x16x32_bf16 v[112:115], v[132:135], v[208:211], 0
	v_mfma_f32_16x16x32_bf16 v[108:111], v[140:143], v[208:211], 0
	v_mfma_f32_16x16x32_bf16 v[96:99], v[132:135], v[216:219], 0
	v_mfma_f32_16x16x32_bf16 v[92:95], v[140:143], v[216:219], 0
	v_mfma_f32_16x16x32_bf16 v[80:83], v[132:135], v[224:227], 0
	v_mfma_f32_16x16x32_bf16 v[76:79], v[140:143], v[224:227], 0
	v_mfma_f32_16x16x32_bf16 v[128:131], v[136:139], v[204:207], v[128:131]
	v_mfma_f32_16x16x32_bf16 v[124:127], v[178:181], v[204:207], v[124:127]
	v_mfma_f32_16x16x32_bf16 v[112:115], v[136:139], v[212:215], v[112:115]
	v_mfma_f32_16x16x32_bf16 v[108:111], v[178:181], v[212:215], v[108:111]
	v_mfma_f32_16x16x32_bf16 v[96:99], v[136:139], v[220:223], v[96:99]
	v_mfma_f32_16x16x32_bf16 v[92:95], v[178:181], v[220:223], v[92:95]
	v_mfma_f32_16x16x32_bf16 v[80:83], v[136:139], v[228:231], v[80:83]
	v_mfma_f32_16x16x32_bf16 v[76:79], v[178:181], v[228:231], v[76:79]
	s_setprio 0
	s_setprio 1
	v_mfma_f32_16x16x32_bf16 v[120:123], v[182:185], v[200:203], 0
	v_mfma_f32_16x16x32_bf16 v[116:119], v[192:195], v[200:203], 0
	v_mfma_f32_16x16x32_bf16 v[104:107], v[182:185], v[208:211], 0
	v_mfma_f32_16x16x32_bf16 v[100:103], v[192:195], v[208:211], 0
	v_mfma_f32_16x16x32_bf16 v[88:91], v[182:185], v[216:219], 0
	v_mfma_f32_16x16x32_bf16 v[84:87], v[192:195], v[216:219], 0
	v_mfma_f32_16x16x32_bf16 v[72:75], v[182:185], v[224:227], 0
	v_mfma_f32_16x16x32_bf16 v[68:71], v[192:195], v[224:227], 0
	v_mfma_f32_16x16x32_bf16 v[120:123], v[188:191], v[204:207], v[120:123]
	v_mfma_f32_16x16x32_bf16 v[116:119], v[196:199], v[204:207], v[116:119]
	v_mfma_f32_16x16x32_bf16 v[104:107], v[188:191], v[212:215], v[104:107]
	v_mfma_f32_16x16x32_bf16 v[100:103], v[196:199], v[212:215], v[100:103]
	v_mfma_f32_16x16x32_bf16 v[88:91], v[188:191], v[220:223], v[88:91]
	v_mfma_f32_16x16x32_bf16 v[84:87], v[196:199], v[220:223], v[84:87]
	v_mfma_f32_16x16x32_bf16 v[72:75], v[188:191], v[228:231], v[72:75]
	v_mfma_f32_16x16x32_bf16 v[68:71], v[196:199], v[228:231], v[68:71]
	s_setprio 0
	s_barrier
	s_add_i32 s75, s79, s68
	v_lshl_add_u64 v[232:233], s[64:65], 0, v[148:149]
	s_mov_b32 m0, s75
	ds_read_b128 v[200:203], v174 offset:16384
	ds_read_b128 v[204:207], v174 offset:17408
	ds_read_b128 v[208:211], v174 offset:18432
	ds_read_b128 v[212:215], v174 offset:19456
	ds_read_b128 v[216:219], v174 offset:20480
	ds_read_b128 v[220:223], v174 offset:21504
	ds_read_b128 v[224:227], v174 offset:22528
	ds_read_b128 v[228:231], v174 offset:23552
	global_load_lds_dwordx4 v[232:233], off
	s_add_i32 m0, s75, 0x2000
	s_add_u32 s92, s64, 0xa0000
	v_lshl_add_u64 v[234:235], s[64:65], 0, v[144:145]
	s_addc_u32 s93, s65, 0
	s_add_i32 s75, s80, s68
	global_load_lds_dwordx4 v[234:235], off
	v_lshl_add_u64 v[2:3], s[92:93], 0, v[148:149]
	s_mov_b32 m0, s75
	v_lshl_add_u64 v[236:237], s[66:67], 0, v[150:151]
	global_load_lds_dwordx4 v[2:3], off
	v_lshl_add_u64 v[2:3], s[92:93], 0, v[144:145]
	s_add_i32 m0, s75, 0x2000
	v_lshl_add_u64 v[238:239], s[66:67], 0, v[146:147]
	global_load_lds_dwordx4 v[2:3], off
	s_mov_b32 m0, s69
	s_nop 0
	global_load_lds_dwordx4 v[236:237], off
	s_mov_b32 m0, s70
	s_nop 0
	global_load_lds_dwordx4 v[238:239], off
	s_waitcnt vmcnt(8)
	s_waitcnt lgkmcnt(0)
	s_waitcnt lgkmcnt(0)
	s_barrier
	s_setprio 1
	v_mfma_f32_16x16x32_bf16 v[64:67], v[132:135], v[200:203], 0
	v_mfma_f32_16x16x32_bf16 v[60:63], v[140:143], v[200:203], 0
	v_mfma_f32_16x16x32_bf16 v[48:51], v[132:135], v[208:211], 0
	v_mfma_f32_16x16x32_bf16 v[44:47], v[140:143], v[208:211], 0
	v_mfma_f32_16x16x32_bf16 v[32:35], v[132:135], v[216:219], 0
	v_mfma_f32_16x16x32_bf16 v[28:31], v[140:143], v[216:219], 0
	v_mfma_f32_16x16x32_bf16 v[16:19], v[132:135], v[224:227], 0
	v_mfma_f32_16x16x32_bf16 v[12:15], v[140:143], v[224:227], 0
	v_mfma_f32_16x16x32_bf16 v[64:67], v[136:139], v[204:207], v[64:67]
	v_mfma_f32_16x16x32_bf16 v[60:63], v[178:181], v[204:207], v[60:63]
	v_mfma_f32_16x16x32_bf16 v[48:51], v[136:139], v[212:215], v[48:51]
	v_mfma_f32_16x16x32_bf16 v[44:47], v[178:181], v[212:215], v[44:47]
	v_mfma_f32_16x16x32_bf16 v[32:35], v[136:139], v[220:223], v[32:35]
	v_mfma_f32_16x16x32_bf16 v[28:31], v[178:181], v[220:223], v[28:31]
	v_mfma_f32_16x16x32_bf16 v[16:19], v[136:139], v[228:231], v[16:19]
	v_mfma_f32_16x16x32_bf16 v[12:15], v[178:181], v[228:231], v[12:15]
	s_setprio 0
	s_setprio 1
	v_mfma_f32_16x16x32_bf16 v[56:59], v[182:185], v[200:203], 0
	v_mfma_f32_16x16x32_bf16 v[52:55], v[192:195], v[200:203], 0
	v_mfma_f32_16x16x32_bf16 v[40:43], v[182:185], v[208:211], 0
	v_mfma_f32_16x16x32_bf16 v[36:39], v[192:195], v[208:211], 0
	v_mfma_f32_16x16x32_bf16 v[24:27], v[182:185], v[216:219], 0
	v_mfma_f32_16x16x32_bf16 v[20:23], v[192:195], v[216:219], 0
	v_mfma_f32_16x16x32_bf16 v[8:11], v[182:185], v[224:227], 0
	v_mfma_f32_16x16x32_bf16 v[2:5], v[192:195], v[224:227], 0
	v_mfma_f32_16x16x32_bf16 v[56:59], v[188:191], v[204:207], v[56:59]
	v_mfma_f32_16x16x32_bf16 v[52:55], v[196:199], v[204:207], v[52:55]
	v_mfma_f32_16x16x32_bf16 v[40:43], v[188:191], v[212:215], v[40:43]
	v_mfma_f32_16x16x32_bf16 v[36:39], v[196:199], v[212:215], v[36:39]
	v_mfma_f32_16x16x32_bf16 v[24:27], v[188:191], v[220:223], v[24:27]
	v_mfma_f32_16x16x32_bf16 v[20:23], v[196:199], v[220:223], v[20:23]
	v_mfma_f32_16x16x32_bf16 v[8:11], v[188:191], v[228:231], v[8:11]
	v_mfma_f32_16x16x32_bf16 v[2:5], v[196:199], v[228:231], v[2:5]
	s_setprio 0
	s_barrier
	s_branch .Lpeel_mid_p3
	s_nop 0
	s_nop 0
	s_nop 0
	s_nop 0
	s_nop 0
	s_nop 0
	s_nop 0
	s_nop 0
	s_nop 0
	s_nop 0
	s_nop 0
	s_nop 0

.LBB0_599:
	v_add_u32_e32 v1, s79, v173
	s_add_i32 s2, s64, 2
	ds_read_b128 v[132:135], v1
	ds_read_b128 v[136:139], v1 offset:1024
	ds_read_b128 v[140:143], v1 offset:2048
	ds_read_b128 v[178:181], v1 offset:3072
	v_add_u32_e32 v1, s80, v173
	s_add_u32 s65, s58, s60
	ds_read_b128 v[182:185], v1
	ds_read_b128 v[188:191], v1 offset:1024
	ds_read_b128 v[192:195], v1 offset:2048
	ds_read_b128 v[196:199], v1 offset:3072
	s_addc_u32 s66, s59, s61
	s_add_u32 s65, s65, 0x100
	s_addc_u32 s66, s66, 0
	s_add_u32 s75, s89, s60
	s_addc_u32 s91, s90, s61
	s_cmp_eq_u32 s7, s64
	s_cselect_b32 s67, s51, s66
	s_cselect_b32 s66, s50, s65
	s_cselect_b32 s65, s53, s91
	s_cselect_b32 s64, s52, s75
	v_lshl_add_u64 v[2:3], v[168:169], 0, s[60:61]
	s_add_i32 m0, s69, 0xc000
	ds_read_b128 v[200:203], v174
	ds_read_b128 v[204:207], v174 offset:1024
	ds_read_b128 v[208:211], v174 offset:2048
	ds_read_b128 v[212:215], v174 offset:3072
	ds_read_b128 v[216:219], v174 offset:4096
	ds_read_b128 v[220:223], v174 offset:5120
	ds_read_b128 v[224:227], v174 offset:6144
	ds_read_b128 v[228:231], v174 offset:7168
	global_load_lds_dwordx4 v[2:3], off
	v_lshl_add_u64 v[2:3], v[170:171], 0, s[60:61]
	s_add_i32 m0, s69, 0xe000
	s_nop 0
	global_load_lds_dwordx4 v[2:3], off
	s_waitcnt vmcnt(8)
	s_waitcnt lgkmcnt(0)
	s_waitcnt lgkmcnt(0)
	s_barrier
	s_setprio 1
	v_mfma_f32_16x16x32_bf16 v[128:131], v[132:135], v[200:203], v[128:131]
	v_mfma_f32_16x16x32_bf16 v[124:127], v[140:143], v[200:203], v[124:127]
	v_mfma_f32_16x16x32_bf16 v[112:115], v[132:135], v[208:211], v[112:115]
	v_mfma_f32_16x16x32_bf16 v[108:111], v[140:143], v[208:211], v[108:111]
	v_mfma_f32_16x16x32_bf16 v[96:99], v[132:135], v[216:219], v[96:99]
	v_mfma_f32_16x16x32_bf16 v[92:95], v[140:143], v[216:219], v[92:95]
	v_mfma_f32_16x16x32_bf16 v[80:83], v[132:135], v[224:227], v[80:83]
	v_mfma_f32_16x16x32_bf16 v[76:79], v[140:143], v[224:227], v[76:79]
	v_mfma_f32_16x16x32_bf16 v[128:131], v[136:139], v[204:207], v[128:131]
	v_mfma_f32_16x16x32_bf16 v[124:127], v[178:181], v[204:207], v[124:127]
	v_mfma_f32_16x16x32_bf16 v[112:115], v[136:139], v[212:215], v[112:115]
	v_mfma_f32_16x16x32_bf16 v[108:111], v[178:181], v[212:215], v[108:111]
	v_mfma_f32_16x16x32_bf16 v[96:99], v[136:139], v[220:223], v[96:99]
	v_mfma_f32_16x16x32_bf16 v[92:95], v[178:181], v[220:223], v[92:95]
	v_mfma_f32_16x16x32_bf16 v[80:83], v[136:139], v[228:231], v[80:83]
	v_mfma_f32_16x16x32_bf16 v[76:79], v[178:181], v[228:231], v[76:79]
	s_setprio 0
	s_setprio 1
	v_mfma_f32_16x16x32_bf16 v[120:123], v[182:185], v[200:203], v[120:123]
	v_mfma_f32_16x16x32_bf16 v[116:119], v[192:195], v[200:203], v[116:119]
	v_mfma_f32_16x16x32_bf16 v[104:107], v[182:185], v[208:211], v[104:107]
	v_mfma_f32_16x16x32_bf16 v[100:103], v[192:195], v[208:211], v[100:103]
	v_mfma_f32_16x16x32_bf16 v[88:91], v[182:185], v[216:219], v[88:91]
	v_mfma_f32_16x16x32_bf16 v[84:87], v[192:195], v[216:219], v[84:87]
	v_mfma_f32_16x16x32_bf16 v[72:75], v[182:185], v[224:227], v[72:75]
	v_mfma_f32_16x16x32_bf16 v[68:71], v[192:195], v[224:227], v[68:71]
	v_mfma_f32_16x16x32_bf16 v[120:123], v[188:191], v[204:207], v[120:123]
	v_mfma_f32_16x16x32_bf16 v[116:119], v[196:199], v[204:207], v[116:119]
	v_mfma_f32_16x16x32_bf16 v[104:107], v[188:191], v[212:215], v[104:107]
	v_mfma_f32_16x16x32_bf16 v[100:103], v[196:199], v[212:215], v[100:103]
	v_mfma_f32_16x16x32_bf16 v[88:91], v[188:191], v[220:223], v[88:91]
	v_mfma_f32_16x16x32_bf16 v[84:87], v[196:199], v[220:223], v[84:87]
	v_mfma_f32_16x16x32_bf16 v[72:75], v[188:191], v[228:231], v[72:75]
	v_mfma_f32_16x16x32_bf16 v[68:71], v[196:199], v[228:231], v[68:71]
	s_setprio 0
	s_barrier
	s_add_i32 s75, s79, s68
	v_lshl_add_u64 v[232:233], s[64:65], 0, v[148:149]
	s_mov_b32 m0, s75
	ds_read_b128 v[200:203], v174 offset:16384
	ds_read_b128 v[204:207], v174 offset:17408
	ds_read_b128 v[208:211], v174 offset:18432
	ds_read_b128 v[212:215], v174 offset:19456
	ds_read_b128 v[216:219], v174 offset:20480
	ds_read_b128 v[220:223], v174 offset:21504
	ds_read_b128 v[224:227], v174 offset:22528
	ds_read_b128 v[228:231], v174 offset:23552
	global_load_lds_dwordx4 v[232:233], off
	s_add_i32 m0, s75, 0x2000
	s_add_u32 s92, s64, 0xa0000
	v_lshl_add_u64 v[234:235], s[64:65], 0, v[144:145]
	s_addc_u32 s93, s65, 0
	s_add_i32 s75, s80, s68
	global_load_lds_dwordx4 v[234:235], off
	v_lshl_add_u64 v[2:3], s[92:93], 0, v[148:149]
	s_mov_b32 m0, s75
	v_lshl_add_u64 v[236:237], s[66:67], 0, v[150:151]
	global_load_lds_dwordx4 v[2:3], off
	v_lshl_add_u64 v[2:3], s[92:93], 0, v[144:145]
	s_add_i32 m0, s75, 0x2000
	v_lshl_add_u64 v[238:239], s[66:67], 0, v[146:147]
	global_load_lds_dwordx4 v[2:3], off
	s_mov_b32 m0, s69
	s_nop 0
	global_load_lds_dwordx4 v[236:237], off
	s_mov_b32 m0, s70
	s_nop 0
	global_load_lds_dwordx4 v[238:239], off
	s_waitcnt vmcnt(8)
	s_waitcnt lgkmcnt(0)
	s_waitcnt lgkmcnt(0)
	s_barrier
	s_setprio 1
	v_mfma_f32_16x16x32_bf16 v[64:67], v[132:135], v[200:203], v[64:67]
	v_mfma_f32_16x16x32_bf16 v[60:63], v[140:143], v[200:203], v[60:63]
	v_mfma_f32_16x16x32_bf16 v[48:51], v[132:135], v[208:211], v[48:51]
	v_mfma_f32_16x16x32_bf16 v[44:47], v[140:143], v[208:211], v[44:47]
	v_mfma_f32_16x16x32_bf16 v[32:35], v[132:135], v[216:219], v[32:35]
	v_mfma_f32_16x16x32_bf16 v[28:31], v[140:143], v[216:219], v[28:31]
	v_mfma_f32_16x16x32_bf16 v[16:19], v[132:135], v[224:227], v[16:19]
	v_mfma_f32_16x16x32_bf16 v[12:15], v[140:143], v[224:227], v[12:15]
	v_mfma_f32_16x16x32_bf16 v[64:67], v[136:139], v[204:207], v[64:67]
	v_mfma_f32_16x16x32_bf16 v[60:63], v[178:181], v[204:207], v[60:63]
	v_mfma_f32_16x16x32_bf16 v[48:51], v[136:139], v[212:215], v[48:51]
	v_mfma_f32_16x16x32_bf16 v[44:47], v[178:181], v[212:215], v[44:47]
	v_mfma_f32_16x16x32_bf16 v[32:35], v[136:139], v[220:223], v[32:35]
	v_mfma_f32_16x16x32_bf16 v[28:31], v[178:181], v[220:223], v[28:31]
	v_mfma_f32_16x16x32_bf16 v[16:19], v[136:139], v[228:231], v[16:19]
	v_mfma_f32_16x16x32_bf16 v[12:15], v[178:181], v[228:231], v[12:15]
	s_setprio 0
	s_setprio 1
	v_mfma_f32_16x16x32_bf16 v[56:59], v[182:185], v[200:203], v[56:59]
	v_mfma_f32_16x16x32_bf16 v[52:55], v[192:195], v[200:203], v[52:55]
	v_mfma_f32_16x16x32_bf16 v[40:43], v[182:185], v[208:211], v[40:43]
	v_mfma_f32_16x16x32_bf16 v[36:39], v[192:195], v[208:211], v[36:39]
	v_mfma_f32_16x16x32_bf16 v[24:27], v[182:185], v[216:219], v[24:27]
	v_mfma_f32_16x16x32_bf16 v[20:23], v[192:195], v[216:219], v[20:23]
	v_mfma_f32_16x16x32_bf16 v[8:11], v[182:185], v[224:227], v[8:11]
	v_mfma_f32_16x16x32_bf16 v[2:5], v[192:195], v[224:227], v[4:7]
	v_mfma_f32_16x16x32_bf16 v[56:59], v[188:191], v[204:207], v[56:59]
	v_mfma_f32_16x16x32_bf16 v[52:55], v[196:199], v[204:207], v[52:55]
	v_mfma_f32_16x16x32_bf16 v[40:43], v[188:191], v[212:215], v[40:43]
	v_mfma_f32_16x16x32_bf16 v[36:39], v[196:199], v[212:215], v[36:39]
	v_mfma_f32_16x16x32_bf16 v[24:27], v[188:191], v[220:223], v[24:27]
	v_mfma_f32_16x16x32_bf16 v[20:23], v[196:199], v[220:223], v[20:23]
	v_mfma_f32_16x16x32_bf16 v[8:11], v[188:191], v[228:231], v[8:11]
	v_mfma_f32_16x16x32_bf16 v[2:5], v[196:199], v[228:231], v[2:5]
	s_setprio 0
	s_barrier
.Lpeel_mid_p3:
	s_add_i32 s75, 0, 0x18000
	v_add_u32_e32 v1, s75, v173
	s_add_i32 s91, 0, 0x1c000
	ds_read_b128 v[132:135], v1
	ds_read_b128 v[136:139], v1 offset:1024
	ds_read_b128 v[140:143], v1 offset:2048
	ds_read_b128 v[178:181], v1 offset:3072
	v_add_u32_e32 v1, s91, v173
	ds_read_b128 v[182:185], v1
	ds_read_b128 v[188:191], v1 offset:1024
	ds_read_b128 v[192:195], v1 offset:2048
	ds_read_b128 v[196:199], v1 offset:3072
	s_add_u32 s66, s66, 0xa0000
	s_addc_u32 s67, s67, 0
	s_mov_b32 m0, s71
	v_lshl_add_u64 v[6:7], s[66:67], 0, v[150:151]
	ds_read_b128 v[200:203], v174 offset:32768
	ds_read_b128 v[204:207], v174 offset:33792
	ds_read_b128 v[208:211], v174 offset:34816
	ds_read_b128 v[212:215], v174 offset:35840
	ds_read_b128 v[216:219], v174 offset:36864
	ds_read_b128 v[220:223], v174 offset:37888
	ds_read_b128 v[224:227], v174 offset:38912
	ds_read_b128 v[228:231], v174 offset:39936
	global_load_lds_dwordx4 v[6:7], off
	v_lshl_add_u64 v[6:7], s[66:67], 0, v[146:147]
	s_mov_b32 m0, s72
	s_nop 0
	global_load_lds_dwordx4 v[6:7], off
	s_waitcnt vmcnt(8)
	s_waitcnt lgkmcnt(0)
	s_waitcnt lgkmcnt(0)
	s_barrier
	s_setprio 1
	v_mfma_f32_16x16x32_bf16 v[128:131], v[132:135], v[200:203], v[128:131]
	v_mfma_f32_16x16x32_bf16 v[124:127], v[140:143], v[200:203], v[124:127]
	v_mfma_f32_16x16x32_bf16 v[112:115], v[132:135], v[208:211], v[112:115]
	v_mfma_f32_16x16x32_bf16 v[108:111], v[140:143], v[208:211], v[108:111]
	v_mfma_f32_16x16x32_bf16 v[96:99], v[132:135], v[216:219], v[96:99]
	v_mfma_f32_16x16x32_bf16 v[92:95], v[140:143], v[216:219], v[92:95]
	v_mfma_f32_16x16x32_bf16 v[80:83], v[132:135], v[224:227], v[80:83]
	v_mfma_f32_16x16x32_bf16 v[76:79], v[140:143], v[224:227], v[76:79]
	v_mfma_f32_16x16x32_bf16 v[128:131], v[136:139], v[204:207], v[128:131]
	v_mfma_f32_16x16x32_bf16 v[124:127], v[178:181], v[204:207], v[124:127]
	v_mfma_f32_16x16x32_bf16 v[112:115], v[136:139], v[212:215], v[112:115]
	v_mfma_f32_16x16x32_bf16 v[108:111], v[178:181], v[212:215], v[108:111]
	v_mfma_f32_16x16x32_bf16 v[96:99], v[136:139], v[220:223], v[96:99]
	v_mfma_f32_16x16x32_bf16 v[92:95], v[178:181], v[220:223], v[92:95]
	v_mfma_f32_16x16x32_bf16 v[80:83], v[136:139], v[228:231], v[80:83]
	v_mfma_f32_16x16x32_bf16 v[76:79], v[178:181], v[228:231], v[76:79]
	s_setprio 0
	s_setprio 1
	v_mfma_f32_16x16x32_bf16 v[120:123], v[182:185], v[200:203], v[120:123]
	v_mfma_f32_16x16x32_bf16 v[116:119], v[192:195], v[200:203], v[116:119]
	v_mfma_f32_16x16x32_bf16 v[104:107], v[182:185], v[208:211], v[104:107]
	v_mfma_f32_16x16x32_bf16 v[100:103], v[192:195], v[208:211], v[100:103]
	v_mfma_f32_16x16x32_bf16 v[88:91], v[182:185], v[216:219], v[88:91]
	v_mfma_f32_16x16x32_bf16 v[84:87], v[192:195], v[216:219], v[84:87]
	v_mfma_f32_16x16x32_bf16 v[72:75], v[182:185], v[224:227], v[72:75]
	v_mfma_f32_16x16x32_bf16 v[68:71], v[192:195], v[224:227], v[68:71]
	v_mfma_f32_16x16x32_bf16 v[120:123], v[188:191], v[204:207], v[120:123]
	v_mfma_f32_16x16x32_bf16 v[116:119], v[196:199], v[204:207], v[116:119]
	v_mfma_f32_16x16x32_bf16 v[104:107], v[188:191], v[212:215], v[104:107]
	v_mfma_f32_16x16x32_bf16 v[100:103], v[196:199], v[212:215], v[100:103]
	v_mfma_f32_16x16x32_bf16 v[88:91], v[188:191], v[220:223], v[88:91]
	v_mfma_f32_16x16x32_bf16 v[84:87], v[196:199], v[220:223], v[84:87]
	v_mfma_f32_16x16x32_bf16 v[72:75], v[188:191], v[228:231], v[72:75]
	v_mfma_f32_16x16x32_bf16 v[68:71], v[196:199], v[228:231], v[68:71]
	s_setprio 0
	s_barrier
	s_add_i32 s66, s75, s68
	v_lshl_add_u64 v[6:7], v[232:233], 0, s[14:15]
	s_mov_b32 m0, s66
	ds_read_b128 v[200:203], v174 offset:49152
	ds_read_b128 v[204:207], v174 offset:50176
	ds_read_b128 v[208:211], v174 offset:51200
	ds_read_b128 v[212:215], v174 offset:52224
	ds_read_b128 v[216:219], v174 offset:53248
	ds_read_b128 v[220:223], v174 offset:54272
	ds_read_b128 v[224:227], v174 offset:55296
	ds_read_b128 v[228:231], v174 offset:56320
	global_load_lds_dwordx4 v[6:7], off
	s_add_i32 m0, s66, 0x2000
	s_add_u32 s64, s64, 0xa0080
	v_lshl_add_u64 v[6:7], v[234:235], 0, s[14:15]
	s_addc_u32 s65, s65, 0
	s_add_i32 s66, s91, s68
	global_load_lds_dwordx4 v[6:7], off
	v_lshl_add_u64 v[6:7], s[64:65], 0, v[148:149]
	s_mov_b32 m0, s66
	s_nop 0
	global_load_lds_dwordx4 v[6:7], off
	v_lshl_add_u64 v[6:7], s[64:65], 0, v[144:145]
	s_add_i32 m0, s66, 0x2000
	s_nop 0
	global_load_lds_dwordx4 v[6:7], off
	v_lshl_add_u64 v[6:7], v[236:237], 0, s[14:15]
	s_mov_b32 m0, s73
	s_nop 0
	global_load_lds_dwordx4 v[6:7], off
	v_lshl_add_u64 v[6:7], v[238:239], 0, s[14:15]
	s_mov_b32 m0, s76
	s_nop 0
	global_load_lds_dwordx4 v[6:7], off
	s_waitcnt vmcnt(8)
	s_waitcnt lgkmcnt(0)
	s_waitcnt lgkmcnt(0)
	s_barrier
	s_setprio 1
	v_mfma_f32_16x16x32_bf16 v[64:67], v[132:135], v[200:203], v[64:67]
	v_mfma_f32_16x16x32_bf16 v[60:63], v[140:143], v[200:203], v[60:63]
	v_mfma_f32_16x16x32_bf16 v[48:51], v[132:135], v[208:211], v[48:51]
	v_mfma_f32_16x16x32_bf16 v[44:47], v[140:143], v[208:211], v[44:47]
	v_mfma_f32_16x16x32_bf16 v[32:35], v[132:135], v[216:219], v[32:35]
	v_mfma_f32_16x16x32_bf16 v[28:31], v[140:143], v[216:219], v[28:31]
	v_mfma_f32_16x16x32_bf16 v[16:19], v[132:135], v[224:227], v[16:19]
	v_mfma_f32_16x16x32_bf16 v[12:15], v[140:143], v[224:227], v[12:15]
	v_mfma_f32_16x16x32_bf16 v[64:67], v[136:139], v[204:207], v[64:67]
	v_mfma_f32_16x16x32_bf16 v[60:63], v[178:181], v[204:207], v[60:63]
	v_mfma_f32_16x16x32_bf16 v[48:51], v[136:139], v[212:215], v[48:51]
	v_mfma_f32_16x16x32_bf16 v[44:47], v[178:181], v[212:215], v[44:47]
	v_mfma_f32_16x16x32_bf16 v[32:35], v[136:139], v[220:223], v[32:35]
	v_mfma_f32_16x16x32_bf16 v[28:31], v[178:181], v[220:223], v[28:31]
	v_mfma_f32_16x16x32_bf16 v[16:19], v[136:139], v[228:231], v[16:19]
	v_mfma_f32_16x16x32_bf16 v[12:15], v[178:181], v[228:231], v[12:15]
	s_setprio 0
	s_setprio 1
	v_mfma_f32_16x16x32_bf16 v[56:59], v[182:185], v[200:203], v[56:59]
	v_mfma_f32_16x16x32_bf16 v[52:55], v[192:195], v[200:203], v[52:55]
	v_mfma_f32_16x16x32_bf16 v[40:43], v[182:185], v[208:211], v[40:43]
	v_mfma_f32_16x16x32_bf16 v[36:39], v[192:195], v[208:211], v[36:39]
	v_mfma_f32_16x16x32_bf16 v[24:27], v[182:185], v[216:219], v[24:27]
	v_mfma_f32_16x16x32_bf16 v[20:23], v[192:195], v[216:219], v[20:23]
	v_mfma_f32_16x16x32_bf16 v[6:9], v[182:185], v[224:227], v[8:11]
	v_mfma_f32_16x16x32_bf16 v[2:5], v[192:195], v[224:227], v[2:5]
	v_mfma_f32_16x16x32_bf16 v[56:59], v[188:191], v[204:207], v[56:59]
	v_mfma_f32_16x16x32_bf16 v[52:55], v[196:199], v[204:207], v[52:55]
	v_mfma_f32_16x16x32_bf16 v[40:43], v[188:191], v[212:215], v[40:43]
	v_mfma_f32_16x16x32_bf16 v[36:39], v[196:199], v[212:215], v[36:39]
	v_mfma_f32_16x16x32_bf16 v[24:27], v[188:191], v[220:223], v[24:27]
	v_mfma_f32_16x16x32_bf16 v[20:23], v[196:199], v[220:223], v[20:23]
	v_mfma_f32_16x16x32_bf16 v[8:11], v[188:191], v[228:231], v[6:9]
	v_mfma_f32_16x16x32_bf16 v[4:7], v[196:199], v[228:231], v[2:5]
	s_setprio 0
	s_and_b64 vcc, exec, s[18:19]
	s_cbranch_vccnz .Lhk_skipB
	s_and_b64 vcc, exec, s[62:63]
	s_cbranch_vccnz .Lhk_skipB
	s_cmp_eq_u32 s2, 16
	s_cbranch_scc1 .Lhk_doB
	s_cmp_eq_u32 s2, 24
	s_cbranch_scc0 .Lhk_skipB

.LBB0_671:
	s_add_u32 s6, s6, 0x80080
	s_addc_u32 s7, s7, 0
	s_add_u32 s5, s40, 0x100
	s_addc_u32 s25, s41, 0
	s_mov_b32 s56, -2
	ds_read_b128 v[128:131], v185
	ds_read_b128 v[132:135], v185 offset:1024
	ds_read_b128 v[136:139], v185 offset:2048
	ds_read_b128 v[140:143], v185 offset:3072
	ds_read_b128 v[162:165], v186
	ds_read_b128 v[166:169], v186 offset:1024
	ds_read_b128 v[170:173], v186 offset:2048
	ds_read_b128 v[174:177], v186 offset:3072
	s_add_u32 s38, s6, 0xfff80080
	s_addc_u32 s39, s7, -1
	s_cmp_eq_u32 s56, 28
	s_cselect_b32 s41, s27, s39
	s_cselect_b32 s40, s26, s38
	s_cselect_b32 s39, s23, s25
	s_cselect_b32 s38, s22, s5
	v_lshl_add_u64 v[182:183], s[6:7], 0, v[158:159]
	s_add_i32 m0, s42, 0xc000
	ds_read_b128 v[178:181], v188
	ds_read_b128 v[192:195], v188 offset:1024
	ds_read_b128 v[196:199], v188 offset:2048
	ds_read_b128 v[200:203], v188 offset:3072
	ds_read_b128 v[204:207], v188 offset:4096
	ds_read_b128 v[208:211], v188 offset:5120
	ds_read_b128 v[212:215], v188 offset:6144
	ds_read_b128 v[216:219], v188 offset:7168
	global_load_lds_dwordx4 v[182:183], off
	v_lshl_add_u64 v[182:183], s[6:7], 0, v[160:161]
	s_add_i32 m0, s42, 0xe000
	s_nop 0
	global_load_lds_dwordx4 v[182:183], off
	s_waitcnt vmcnt(8)
	s_waitcnt lgkmcnt(0)
	s_waitcnt lgkmcnt(0)
	s_barrier
	s_setprio 1
	v_mfma_f32_16x16x32_bf16 v[124:127], v[128:131], v[178:181], 0
	v_mfma_f32_16x16x32_bf16 v[120:123], v[136:139], v[178:181], 0
	v_mfma_f32_16x16x32_bf16 v[108:111], v[128:131], v[196:199], 0
	v_mfma_f32_16x16x32_bf16 v[104:107], v[136:139], v[196:199], 0
	v_mfma_f32_16x16x32_bf16 v[92:95], v[128:131], v[204:207], 0
	v_mfma_f32_16x16x32_bf16 v[88:91], v[136:139], v[204:207], 0
	v_mfma_f32_16x16x32_bf16 v[76:79], v[128:131], v[212:215], 0
	v_mfma_f32_16x16x32_bf16 v[72:75], v[136:139], v[212:215], 0
	v_mfma_f32_16x16x32_bf16 v[124:127], v[132:135], v[192:195], v[124:127]
	v_mfma_f32_16x16x32_bf16 v[120:123], v[140:143], v[192:195], v[120:123]
	v_mfma_f32_16x16x32_bf16 v[108:111], v[132:135], v[200:203], v[108:111]
	v_mfma_f32_16x16x32_bf16 v[104:107], v[140:143], v[200:203], v[104:107]
	v_mfma_f32_16x16x32_bf16 v[92:95], v[132:135], v[208:211], v[92:95]
	v_mfma_f32_16x16x32_bf16 v[88:91], v[140:143], v[208:211], v[88:91]
	v_mfma_f32_16x16x32_bf16 v[76:79], v[132:135], v[216:219], v[76:79]
	v_mfma_f32_16x16x32_bf16 v[72:75], v[140:143], v[216:219], v[72:75]
	s_setprio 0
	s_setprio 1
	v_mfma_f32_16x16x32_bf16 v[116:119], v[162:165], v[178:181], 0
	v_mfma_f32_16x16x32_bf16 v[112:115], v[170:173], v[178:181], 0
	v_mfma_f32_16x16x32_bf16 v[100:103], v[162:165], v[196:199], 0
	v_mfma_f32_16x16x32_bf16 v[96:99], v[170:173], v[196:199], 0
	v_mfma_f32_16x16x32_bf16 v[84:87], v[162:165], v[204:207], 0
	v_mfma_f32_16x16x32_bf16 v[80:83], v[170:173], v[204:207], 0
	v_mfma_f32_16x16x32_bf16 v[68:71], v[162:165], v[212:215], 0
	v_mfma_f32_16x16x32_bf16 v[64:67], v[170:173], v[212:215], 0
	v_mfma_f32_16x16x32_bf16 v[116:119], v[166:169], v[192:195], v[116:119]
	v_mfma_f32_16x16x32_bf16 v[112:115], v[174:177], v[192:195], v[112:115]
	v_mfma_f32_16x16x32_bf16 v[100:103], v[166:169], v[200:203], v[100:103]
	v_mfma_f32_16x16x32_bf16 v[96:99], v[174:177], v[200:203], v[96:99]
	v_mfma_f32_16x16x32_bf16 v[84:87], v[166:169], v[208:211], v[84:87]
	v_mfma_f32_16x16x32_bf16 v[80:83], v[174:177], v[208:211], v[80:83]
	v_mfma_f32_16x16x32_bf16 v[68:71], v[166:169], v[216:219], v[68:71]
	v_mfma_f32_16x16x32_bf16 v[64:67], v[174:177], v[216:219], v[64:67]
	s_setprio 0
	s_barrier
	s_add_i32 s57, s51, s35
	v_lshl_add_u64 v[182:183], s[38:39], 0, v[148:149]
	s_mov_b32 m0, s57
	ds_read_b128 v[178:181], v188 offset:16384
	ds_read_b128 v[192:195], v188 offset:17408
	ds_read_b128 v[196:199], v188 offset:18432
	ds_read_b128 v[200:203], v188 offset:19456
	ds_read_b128 v[204:207], v188 offset:20480
	ds_read_b128 v[208:211], v188 offset:21504
	ds_read_b128 v[212:215], v188 offset:22528
	ds_read_b128 v[216:219], v188 offset:23552
	global_load_lds_dwordx4 v[182:183], off
	s_add_i32 m0, s57, 0x2000
	s_add_u32 s58, s38, 0x80000
	v_lshl_add_u64 v[220:221], s[38:39], 0, v[144:145]
	s_addc_u32 s59, s39, 0
	s_add_i32 s57, s52, s35
	global_load_lds_dwordx4 v[220:221], off
	v_lshl_add_u64 v[222:223], s[58:59], 0, v[148:149]
	s_mov_b32 m0, s57
	v_lshl_add_u64 v[224:225], s[40:41], 0, v[146:147]
	global_load_lds_dwordx4 v[222:223], off
	v_lshl_add_u64 v[222:223], s[58:59], 0, v[144:145]
	s_add_i32 m0, s57, 0x2000
	s_nop 0
	global_load_lds_dwordx4 v[222:223], off
	v_lshl_add_u64 v[222:223], s[40:41], 0, v[150:151]
	s_mov_b32 m0, s42
	s_nop 0
	global_load_lds_dwordx4 v[222:223], off
	s_mov_b32 m0, s43
	s_nop 0
	global_load_lds_dwordx4 v[224:225], off
	s_waitcnt vmcnt(8)
	s_waitcnt lgkmcnt(0)
	s_waitcnt lgkmcnt(0)
	s_barrier
	s_setprio 1
	v_mfma_f32_16x16x32_bf16 v[60:63], v[128:131], v[178:181], 0
	v_mfma_f32_16x16x32_bf16 v[56:59], v[136:139], v[178:181], 0
	v_mfma_f32_16x16x32_bf16 v[44:47], v[128:131], v[196:199], 0
	v_mfma_f32_16x16x32_bf16 v[40:43], v[136:139], v[196:199], 0
	v_mfma_f32_16x16x32_bf16 v[28:31], v[128:131], v[204:207], 0
	v_mfma_f32_16x16x32_bf16 v[24:27], v[136:139], v[204:207], 0
	v_mfma_f32_16x16x32_bf16 v[12:15], v[128:131], v[212:215], 0
	v_mfma_f32_16x16x32_bf16 v[8:11], v[136:139], v[212:215], 0
	v_mfma_f32_16x16x32_bf16 v[60:63], v[132:135], v[192:195], v[60:63]
	v_mfma_f32_16x16x32_bf16 v[56:59], v[140:143], v[192:195], v[56:59]
	v_mfma_f32_16x16x32_bf16 v[44:47], v[132:135], v[200:203], v[44:47]
	v_mfma_f32_16x16x32_bf16 v[40:43], v[140:143], v[200:203], v[40:43]
	v_mfma_f32_16x16x32_bf16 v[28:31], v[132:135], v[208:211], v[28:31]
	v_mfma_f32_16x16x32_bf16 v[24:27], v[140:143], v[208:211], v[24:27]
	v_mfma_f32_16x16x32_bf16 v[12:15], v[132:135], v[216:219], v[12:15]
	v_mfma_f32_16x16x32_bf16 v[8:11], v[140:143], v[216:219], v[8:11]
	s_setprio 0
	s_setprio 1
	v_mfma_f32_16x16x32_bf16 v[52:55], v[162:165], v[178:181], 0
	v_mfma_f32_16x16x32_bf16 v[48:51], v[170:173], v[178:181], 0
	v_mfma_f32_16x16x32_bf16 v[36:39], v[162:165], v[196:199], 0
	v_mfma_f32_16x16x32_bf16 v[32:35], v[170:173], v[196:199], 0
	v_mfma_f32_16x16x32_bf16 v[20:23], v[162:165], v[204:207], 0
	v_mfma_f32_16x16x32_bf16 v[16:19], v[170:173], v[204:207], 0
	v_mfma_f32_16x16x32_bf16 v[4:7], v[162:165], v[212:215], 0
	v_mfma_f32_16x16x32_bf16 v[0:3], v[170:173], v[212:215], 0
	v_mfma_f32_16x16x32_bf16 v[52:55], v[166:169], v[192:195], v[52:55]
	v_mfma_f32_16x16x32_bf16 v[48:51], v[174:177], v[192:195], v[48:51]
	v_mfma_f32_16x16x32_bf16 v[36:39], v[166:169], v[200:203], v[36:39]
	v_mfma_f32_16x16x32_bf16 v[32:35], v[174:177], v[200:203], v[32:35]
	v_mfma_f32_16x16x32_bf16 v[20:23], v[166:169], v[208:211], v[20:23]
	v_mfma_f32_16x16x32_bf16 v[16:19], v[174:177], v[208:211], v[16:19]
	v_mfma_f32_16x16x32_bf16 v[4:7], v[166:169], v[216:219], v[4:7]
	v_mfma_f32_16x16x32_bf16 v[0:3], v[174:177], v[216:219], v[0:3]
	s_setprio 0
	s_barrier
	s_branch .Lpeel_mid_p4
.LBB0_672:
	ds_read_b128 v[128:131], v185
	ds_read_b128 v[132:135], v185 offset:1024
	ds_read_b128 v[136:139], v185 offset:2048
	ds_read_b128 v[140:143], v185 offset:3072
	ds_read_b128 v[162:165], v186
	ds_read_b128 v[166:169], v186 offset:1024
	ds_read_b128 v[170:173], v186 offset:2048
	ds_read_b128 v[174:177], v186 offset:3072
	s_add_u32 s38, s6, 0xfff80080
	s_addc_u32 s39, s7, -1
	s_cmp_eq_u32 s56, 28
	s_cselect_b32 s41, s27, s39
	s_cselect_b32 s40, s26, s38
	s_cselect_b32 s39, s23, s25
	s_cselect_b32 s38, s22, s5
	v_lshl_add_u64 v[182:183], s[6:7], 0, v[158:159]
	s_add_i32 m0, s42, 0xc000
	ds_read_b128 v[178:181], v188
	ds_read_b128 v[192:195], v188 offset:1024
	ds_read_b128 v[196:199], v188 offset:2048
	ds_read_b128 v[200:203], v188 offset:3072
	ds_read_b128 v[204:207], v188 offset:4096
	ds_read_b128 v[208:211], v188 offset:5120
	ds_read_b128 v[212:215], v188 offset:6144
	ds_read_b128 v[216:219], v188 offset:7168
	global_load_lds_dwordx4 v[182:183], off
	v_lshl_add_u64 v[182:183], s[6:7], 0, v[160:161]
	s_add_i32 m0, s42, 0xe000
	s_nop 0
	global_load_lds_dwordx4 v[182:183], off
	s_waitcnt vmcnt(8)
	s_waitcnt lgkmcnt(0)
	s_waitcnt lgkmcnt(0)
	s_barrier
	s_setprio 1
	v_mfma_f32_16x16x32_bf16 v[124:127], v[128:131], v[178:181], v[124:127]
	v_mfma_f32_16x16x32_bf16 v[120:123], v[136:139], v[178:181], v[120:123]
	v_mfma_f32_16x16x32_bf16 v[108:111], v[128:131], v[196:199], v[108:111]
	v_mfma_f32_16x16x32_bf16 v[104:107], v[136:139], v[196:199], v[104:107]
	v_mfma_f32_16x16x32_bf16 v[92:95], v[128:131], v[204:207], v[92:95]
	v_mfma_f32_16x16x32_bf16 v[88:91], v[136:139], v[204:207], v[88:91]
	v_mfma_f32_16x16x32_bf16 v[76:79], v[128:131], v[212:215], v[76:79]
	v_mfma_f32_16x16x32_bf16 v[72:75], v[136:139], v[212:215], v[72:75]
	v_mfma_f32_16x16x32_bf16 v[124:127], v[132:135], v[192:195], v[124:127]
	v_mfma_f32_16x16x32_bf16 v[120:123], v[140:143], v[192:195], v[120:123]
	v_mfma_f32_16x16x32_bf16 v[108:111], v[132:135], v[200:203], v[108:111]
	v_mfma_f32_16x16x32_bf16 v[104:107], v[140:143], v[200:203], v[104:107]
	v_mfma_f32_16x16x32_bf16 v[92:95], v[132:135], v[208:211], v[92:95]
	v_mfma_f32_16x16x32_bf16 v[88:91], v[140:143], v[208:211], v[88:91]
	v_mfma_f32_16x16x32_bf16 v[76:79], v[132:135], v[216:219], v[76:79]
	v_mfma_f32_16x16x32_bf16 v[72:75], v[140:143], v[216:219], v[72:75]
	s_setprio 0
	s_setprio 1
	v_mfma_f32_16x16x32_bf16 v[116:119], v[162:165], v[178:181], v[116:119]
	v_mfma_f32_16x16x32_bf16 v[112:115], v[170:173], v[178:181], v[112:115]
	v_mfma_f32_16x16x32_bf16 v[100:103], v[162:165], v[196:199], v[100:103]
	v_mfma_f32_16x16x32_bf16 v[96:99], v[170:173], v[196:199], v[96:99]
	v_mfma_f32_16x16x32_bf16 v[84:87], v[162:165], v[204:207], v[84:87]
	v_mfma_f32_16x16x32_bf16 v[80:83], v[170:173], v[204:207], v[80:83]
	v_mfma_f32_16x16x32_bf16 v[68:71], v[162:165], v[212:215], v[68:71]
	v_mfma_f32_16x16x32_bf16 v[64:67], v[170:173], v[212:215], v[64:67]
	v_mfma_f32_16x16x32_bf16 v[116:119], v[166:169], v[192:195], v[116:119]
	v_mfma_f32_16x16x32_bf16 v[112:115], v[174:177], v[192:195], v[112:115]
	v_mfma_f32_16x16x32_bf16 v[100:103], v[166:169], v[200:203], v[100:103]
	v_mfma_f32_16x16x32_bf16 v[96:99], v[174:177], v[200:203], v[96:99]
	v_mfma_f32_16x16x32_bf16 v[84:87], v[166:169], v[208:211], v[84:87]
	v_mfma_f32_16x16x32_bf16 v[80:83], v[174:177], v[208:211], v[80:83]
	v_mfma_f32_16x16x32_bf16 v[68:71], v[166:169], v[216:219], v[68:71]
	v_mfma_f32_16x16x32_bf16 v[64:67], v[174:177], v[216:219], v[64:67]
	s_setprio 0
	s_barrier
	s_add_i32 s57, s51, s35
	v_lshl_add_u64 v[182:183], s[38:39], 0, v[148:149]
	s_mov_b32 m0, s57
	ds_read_b128 v[178:181], v188 offset:16384
	ds_read_b128 v[192:195], v188 offset:17408
	ds_read_b128 v[196:199], v188 offset:18432
	ds_read_b128 v[200:203], v188 offset:19456
	ds_read_b128 v[204:207], v188 offset:20480
	ds_read_b128 v[208:211], v188 offset:21504
	ds_read_b128 v[212:215], v188 offset:22528
	ds_read_b128 v[216:219], v188 offset:23552
	global_load_lds_dwordx4 v[182:183], off
	s_add_i32 m0, s57, 0x2000
	s_add_u32 s58, s38, 0x80000
	v_lshl_add_u64 v[220:221], s[38:39], 0, v[144:145]
	s_addc_u32 s59, s39, 0
	s_add_i32 s57, s52, s35
	global_load_lds_dwordx4 v[220:221], off
	v_lshl_add_u64 v[222:223], s[58:59], 0, v[148:149]
	s_mov_b32 m0, s57
	v_lshl_add_u64 v[224:225], s[40:41], 0, v[146:147]
	global_load_lds_dwordx4 v[222:223], off
	v_lshl_add_u64 v[222:223], s[58:59], 0, v[144:145]
	s_add_i32 m0, s57, 0x2000
	s_nop 0
	global_load_lds_dwordx4 v[222:223], off
	v_lshl_add_u64 v[222:223], s[40:41], 0, v[150:151]
	s_mov_b32 m0, s42
	s_nop 0
	global_load_lds_dwordx4 v[222:223], off
	s_mov_b32 m0, s43
	s_nop 0
	global_load_lds_dwordx4 v[224:225], off
	s_waitcnt vmcnt(8)
	s_waitcnt lgkmcnt(0)
	s_waitcnt lgkmcnt(0)
	s_barrier
	s_setprio 1
	v_mfma_f32_16x16x32_bf16 v[60:63], v[128:131], v[178:181], v[60:63]
	v_mfma_f32_16x16x32_bf16 v[56:59], v[136:139], v[178:181], v[56:59]
	v_mfma_f32_16x16x32_bf16 v[44:47], v[128:131], v[196:199], v[44:47]
	v_mfma_f32_16x16x32_bf16 v[40:43], v[136:139], v[196:199], v[40:43]
	v_mfma_f32_16x16x32_bf16 v[28:31], v[128:131], v[204:207], v[28:31]
	v_mfma_f32_16x16x32_bf16 v[24:27], v[136:139], v[204:207], v[24:27]
	v_mfma_f32_16x16x32_bf16 v[12:15], v[128:131], v[212:215], v[12:15]
	v_mfma_f32_16x16x32_bf16 v[8:11], v[136:139], v[212:215], v[8:11]
	v_mfma_f32_16x16x32_bf16 v[60:63], v[132:135], v[192:195], v[60:63]
	v_mfma_f32_16x16x32_bf16 v[56:59], v[140:143], v[192:195], v[56:59]
	v_mfma_f32_16x16x32_bf16 v[44:47], v[132:135], v[200:203], v[44:47]
	v_mfma_f32_16x16x32_bf16 v[40:43], v[140:143], v[200:203], v[40:43]
	v_mfma_f32_16x16x32_bf16 v[28:31], v[132:135], v[208:211], v[28:31]
	v_mfma_f32_16x16x32_bf16 v[24:27], v[140:143], v[208:211], v[24:27]
	v_mfma_f32_16x16x32_bf16 v[12:15], v[132:135], v[216:219], v[12:15]
	v_mfma_f32_16x16x32_bf16 v[8:11], v[140:143], v[216:219], v[8:11]
	s_setprio 0
	s_setprio 1
	v_mfma_f32_16x16x32_bf16 v[52:55], v[162:165], v[178:181], v[52:55]
	v_mfma_f32_16x16x32_bf16 v[48:51], v[170:173], v[178:181], v[48:51]
	v_mfma_f32_16x16x32_bf16 v[36:39], v[162:165], v[196:199], v[36:39]
	v_mfma_f32_16x16x32_bf16 v[32:35], v[170:173], v[196:199], v[32:35]
	v_mfma_f32_16x16x32_bf16 v[20:23], v[162:165], v[204:207], v[20:23]
	v_mfma_f32_16x16x32_bf16 v[16:19], v[170:173], v[204:207], v[16:19]
	v_mfma_f32_16x16x32_bf16 v[4:7], v[162:165], v[212:215], v[4:7]
	v_mfma_f32_16x16x32_bf16 v[0:3], v[170:173], v[212:215], v[0:3]
	v_mfma_f32_16x16x32_bf16 v[52:55], v[166:169], v[192:195], v[52:55]
	v_mfma_f32_16x16x32_bf16 v[48:51], v[174:177], v[192:195], v[48:51]
	v_mfma_f32_16x16x32_bf16 v[36:39], v[166:169], v[200:203], v[36:39]
	v_mfma_f32_16x16x32_bf16 v[32:35], v[174:177], v[200:203], v[32:35]
	v_mfma_f32_16x16x32_bf16 v[20:23], v[166:169], v[208:211], v[20:23]
	v_mfma_f32_16x16x32_bf16 v[16:19], v[174:177], v[208:211], v[16:19]
	v_mfma_f32_16x16x32_bf16 v[4:7], v[166:169], v[216:219], v[4:7]
	v_mfma_f32_16x16x32_bf16 v[0:3], v[174:177], v[216:219], v[0:3]
	s_setprio 0
	s_barrier
.Lpeel_mid_p4:
	s_add_i32 s57, 0, 0x18000
	s_add_i32 s58, 0, 0x1c000
	v_add_u32_e32 v140, s57, v184
	v_add_u32_e32 v174, s58, v184
	ds_read_b128 v[128:131], v140
	ds_read_b128 v[132:135], v140 offset:1024
	ds_read_b128 v[136:139], v140 offset:2048
	ds_read_b128 v[140:143], v140 offset:3072
	ds_read_b128 v[162:165], v174
	ds_read_b128 v[166:169], v174 offset:1024
	ds_read_b128 v[170:173], v174 offset:2048
	ds_read_b128 v[174:177], v174 offset:3072
	s_add_u32 s40, s40, 0x80000
	s_addc_u32 s41, s41, 0
	s_mov_b32 m0, s44
	v_lshl_add_u64 v[226:227], s[40:41], 0, v[150:151]
	ds_read_b128 v[178:181], v188 offset:32768
	ds_read_b128 v[192:195], v188 offset:33792
	ds_read_b128 v[196:199], v188 offset:34816
	ds_read_b128 v[200:203], v188 offset:35840
	ds_read_b128 v[204:207], v188 offset:36864
	ds_read_b128 v[208:211], v188 offset:37888
	ds_read_b128 v[212:215], v188 offset:38912
	ds_read_b128 v[216:219], v188 offset:39936
	global_load_lds_dwordx4 v[226:227], off
	v_lshl_add_u64 v[226:227], s[40:41], 0, v[146:147]
	s_mov_b32 m0, s45
	s_nop 0
	global_load_lds_dwordx4 v[226:227], off
	s_waitcnt vmcnt(8)
	s_waitcnt lgkmcnt(0)
	s_waitcnt lgkmcnt(0)
	s_barrier
	s_setprio 1
	v_mfma_f32_16x16x32_bf16 v[124:127], v[128:131], v[178:181], v[124:127]
	v_mfma_f32_16x16x32_bf16 v[120:123], v[136:139], v[178:181], v[120:123]
	v_mfma_f32_16x16x32_bf16 v[108:111], v[128:131], v[196:199], v[108:111]
	v_mfma_f32_16x16x32_bf16 v[104:107], v[136:139], v[196:199], v[104:107]
	v_mfma_f32_16x16x32_bf16 v[92:95], v[128:131], v[204:207], v[92:95]
	v_mfma_f32_16x16x32_bf16 v[88:91], v[136:139], v[204:207], v[88:91]
	v_mfma_f32_16x16x32_bf16 v[76:79], v[128:131], v[212:215], v[76:79]
	v_mfma_f32_16x16x32_bf16 v[72:75], v[136:139], v[212:215], v[72:75]
	v_mfma_f32_16x16x32_bf16 v[124:127], v[132:135], v[192:195], v[124:127]
	v_mfma_f32_16x16x32_bf16 v[120:123], v[140:143], v[192:195], v[120:123]
	v_mfma_f32_16x16x32_bf16 v[108:111], v[132:135], v[200:203], v[108:111]
	v_mfma_f32_16x16x32_bf16 v[104:107], v[140:143], v[200:203], v[104:107]
	v_mfma_f32_16x16x32_bf16 v[92:95], v[132:135], v[208:211], v[92:95]
	v_mfma_f32_16x16x32_bf16 v[88:91], v[140:143], v[208:211], v[88:91]
	v_mfma_f32_16x16x32_bf16 v[76:79], v[132:135], v[216:219], v[76:79]
	v_mfma_f32_16x16x32_bf16 v[72:75], v[140:143], v[216:219], v[72:75]
	s_setprio 0
	s_setprio 1
	v_mfma_f32_16x16x32_bf16 v[116:119], v[162:165], v[178:181], v[116:119]
	v_mfma_f32_16x16x32_bf16 v[112:115], v[170:173], v[178:181], v[112:115]
	v_mfma_f32_16x16x32_bf16 v[100:103], v[162:165], v[196:199], v[100:103]
	v_mfma_f32_16x16x32_bf16 v[96:99], v[170:173], v[196:199], v[96:99]
	v_mfma_f32_16x16x32_bf16 v[84:87], v[162:165], v[204:207], v[84:87]
	v_mfma_f32_16x16x32_bf16 v[80:83], v[170:173], v[204:207], v[80:83]
	v_mfma_f32_16x16x32_bf16 v[68:71], v[162:165], v[212:215], v[68:71]
	v_mfma_f32_16x16x32_bf16 v[64:67], v[170:173], v[212:215], v[64:67]
	v_mfma_f32_16x16x32_bf16 v[116:119], v[166:169], v[192:195], v[116:119]
	v_mfma_f32_16x16x32_bf16 v[112:115], v[174:177], v[192:195], v[112:115]
	v_mfma_f32_16x16x32_bf16 v[100:103], v[166:169], v[200:203], v[100:103]
	v_mfma_f32_16x16x32_bf16 v[96:99], v[174:177], v[200:203], v[96:99]
	v_mfma_f32_16x16x32_bf16 v[84:87], v[166:169], v[208:211], v[84:87]
	v_mfma_f32_16x16x32_bf16 v[80:83], v[174:177], v[208:211], v[80:83]
	v_mfma_f32_16x16x32_bf16 v[68:71], v[166:169], v[216:219], v[68:71]
	v_mfma_f32_16x16x32_bf16 v[64:67], v[174:177], v[216:219], v[64:67]
	s_setprio 0
	s_barrier
	s_add_i32 s40, s57, s35
	v_lshl_add_u64 v[182:183], v[182:183], 0, s[14:15]
	s_mov_b32 m0, s40
	ds_read_b128 v[178:181], v188 offset:49152
	ds_read_b128 v[192:195], v188 offset:50176
	ds_read_b128 v[196:199], v188 offset:51200
	ds_read_b128 v[200:203], v188 offset:52224
	ds_read_b128 v[204:207], v188 offset:53248
	ds_read_b128 v[208:211], v188 offset:54272
	ds_read_b128 v[212:215], v188 offset:55296
	ds_read_b128 v[216:219], v188 offset:56320
	global_load_lds_dwordx4 v[182:183], off
	s_add_i32 m0, s40, 0x2000
	s_add_u32 s38, s38, 0x80080
	v_lshl_add_u64 v[182:183], v[220:221], 0, s[14:15]
	s_addc_u32 s39, s39, 0
	s_add_i32 s40, s58, s35
	global_load_lds_dwordx4 v[182:183], off
	v_lshl_add_u64 v[182:183], s[38:39], 0, v[148:149]
	s_mov_b32 m0, s40
	s_nop 0
	global_load_lds_dwordx4 v[182:183], off
	v_lshl_add_u64 v[182:183], s[38:39], 0, v[144:145]
	s_add_i32 m0, s40, 0x2000
	s_nop 0
	global_load_lds_dwordx4 v[182:183], off
	v_lshl_add_u64 v[182:183], v[222:223], 0, s[14:15]
	s_mov_b32 m0, s49
	s_nop 0
	global_load_lds_dwordx4 v[182:183], off
	v_lshl_add_u64 v[182:183], v[224:225], 0, s[14:15]
	s_mov_b32 m0, s50
	s_nop 0
	global_load_lds_dwordx4 v[182:183], off
	s_waitcnt vmcnt(8)
	s_waitcnt lgkmcnt(0)
	s_waitcnt lgkmcnt(0)
	s_barrier
	s_setprio 1
	v_mfma_f32_16x16x32_bf16 v[60:63], v[128:131], v[178:181], v[60:63]
	v_mfma_f32_16x16x32_bf16 v[56:59], v[136:139], v[178:181], v[56:59]
	v_mfma_f32_16x16x32_bf16 v[44:47], v[128:131], v[196:199], v[44:47]
	v_mfma_f32_16x16x32_bf16 v[40:43], v[136:139], v[196:199], v[40:43]
	v_mfma_f32_16x16x32_bf16 v[28:31], v[128:131], v[204:207], v[28:31]
	v_mfma_f32_16x16x32_bf16 v[24:27], v[136:139], v[204:207], v[24:27]
	v_mfma_f32_16x16x32_bf16 v[12:15], v[128:131], v[212:215], v[12:15]
	v_mfma_f32_16x16x32_bf16 v[8:11], v[136:139], v[212:215], v[8:11]
	v_mfma_f32_16x16x32_bf16 v[60:63], v[132:135], v[192:195], v[60:63]
	v_mfma_f32_16x16x32_bf16 v[56:59], v[140:143], v[192:195], v[56:59]
	v_mfma_f32_16x16x32_bf16 v[44:47], v[132:135], v[200:203], v[44:47]
	v_mfma_f32_16x16x32_bf16 v[40:43], v[140:143], v[200:203], v[40:43]
	v_mfma_f32_16x16x32_bf16 v[28:31], v[132:135], v[208:211], v[28:31]
	v_mfma_f32_16x16x32_bf16 v[24:27], v[140:143], v[208:211], v[24:27]
	v_mfma_f32_16x16x32_bf16 v[12:15], v[132:135], v[216:219], v[12:15]
	v_mfma_f32_16x16x32_bf16 v[8:11], v[140:143], v[216:219], v[8:11]
	s_setprio 0
	s_setprio 1
	v_mfma_f32_16x16x32_bf16 v[52:55], v[162:165], v[178:181], v[52:55]
	v_mfma_f32_16x16x32_bf16 v[48:51], v[170:173], v[178:181], v[48:51]
	v_mfma_f32_16x16x32_bf16 v[36:39], v[162:165], v[196:199], v[36:39]
	v_mfma_f32_16x16x32_bf16 v[32:35], v[170:173], v[196:199], v[32:35]
	v_mfma_f32_16x16x32_bf16 v[20:23], v[162:165], v[204:207], v[20:23]
	v_mfma_f32_16x16x32_bf16 v[16:19], v[170:173], v[204:207], v[16:19]
	v_mfma_f32_16x16x32_bf16 v[4:7], v[162:165], v[212:215], v[4:7]
	v_mfma_f32_16x16x32_bf16 v[0:3], v[170:173], v[212:215], v[0:3]
	v_mfma_f32_16x16x32_bf16 v[52:55], v[166:169], v[192:195], v[52:55]
	v_mfma_f32_16x16x32_bf16 v[48:51], v[174:177], v[192:195], v[48:51]
	v_mfma_f32_16x16x32_bf16 v[36:39], v[166:169], v[200:203], v[36:39]
	v_mfma_f32_16x16x32_bf16 v[32:35], v[174:177], v[200:203], v[32:35]
	v_mfma_f32_16x16x32_bf16 v[20:23], v[166:169], v[208:211], v[20:23]
	v_mfma_f32_16x16x32_bf16 v[16:19], v[174:177], v[208:211], v[16:19]
	v_mfma_f32_16x16x32_bf16 v[4:7], v[166:169], v[216:219], v[4:7]
	v_mfma_f32_16x16x32_bf16 v[0:3], v[174:177], v[216:219], v[0:3]
	s_setprio 0
	s_barrier
	s_add_i32 s56, s56, 2
	s_add_u32 s6, s6, 0x100
	s_addc_u32 s7, s7, 0
	s_add_u32 s5, s5, 0x100
	s_addc_u32 s25, s25, 0
	s_cmp_gt_u32 s56, 29
	s_cbranch_scc0 .LBB0_672
	s_and_b64 vcc, exec, s[18:19]
	s_cbranch_vccz .LBB0_675
	s_barrier
